# GEMM K-loops: first K-iteration peeled, accumulators initialised via MFMA srcC=0 instead of 128 v_mov per unit
# speedup vs baseline: 1.0046x; 1.0046x over previous
; #define PG8_STAGE(bufoff, gbase, voff) do { _Pragma("unroll") for (int _i = 0; _i < 2; ++_i) \
;         __builtin_amdgcn_global_load_lds((const unsigned*)((const char*)(gbase) + (voff)[_i]), (PG8_LAS unsigned*)(lds + (bufoff) + ldsw + _i * 8192), 16, 0, 0); } while (0)
; #define PG8_LDA(dst, b, h) do { _Pragma("unroll") for (int m = 0; m < 4; ++m) _Pragma("unroll") for (int k = 0; k < 2; ++k) dst[m][k] = *(const PG8_LAS bf16x8*)(lds + PG8_SA(b, h) + aoff + m * 2048 + k * 1024); } while (0)
; #define PG8_LDB(dst, b, h) do { _Pragma("unroll") for (int n = 0; n < 2; ++n) _Pragma("unroll") for (int k = 0; k < 2; ++k) dst[n][k] = *(const PG8_LAS bf16x8*)(lds + PG8_SB(b, h) + boff + n * 2048 + k * 1024); } while (0)
; #define PG8_MMA(ai, bj, At, Bt) do { __builtin_amdgcn_s_setprio(1); _Pragma("unroll") for (int m = 0; m < 4; ++m) _Pragma("unroll") for (int n = 0; n < 2; ++n) _Pragma("unroll") for (int k = 0; k < 2; ++k) \
;         acc[ai][bj][m][n] = __builtin_amdgcn_mfma_f32_16x16x32_bf16(Bt[n][k], At[m][k], acc[ai][bj][m][n], 0, 0, 0); __builtin_amdgcn_s_setprio(0); } while (0)
; #define PG8_WAIT_V(n) asm volatile("s_waitcnt vmcnt(" #n ")" ::: "memory")
; #define PG8_WAIT_L(n) asm volatile("s_waitcnt lgkmcnt(" #n ")" ::: "memory")
; #define PG8_BAR __builtin_amdgcn_s_barrier()
; #define PG8_SCHED __builtin_amdgcn_sched_barrier(0)
; template <class Epi, class Sched, bool ALIGN_EPI = false, bool SP2 = false>
; __device__ __forceinline__ void gemm_phase(PG8_LAS unsigned char* lds, const Gemm g, const Sched& S, const Epi& E) {
;     ...
;             PG8_LDB(B0, 0, 0); PG8_LDB(B1, 0, 1); PG8_SCHED; PG8_LDA(At, 0, 0); PG8_STAGE(PG8_SA(1, 1), a1 + hstep, voffA);
;             PG8_WAIT_V(8); PG8_WAIT_L(0); PG8_BAR; PG8_MMA(0, 0, At, B0); PG8_MMA(0, 1, At, B1); PG8_BAR; PG8_SCHED;
;             PG8_LDA(At, 0, 1); PG8_STAGE(PG8_SB(0, 0), b2, voffB); PG8_STAGE(PG8_SB(0, 1), b2 + hstep, voffB); PG8_STAGE(PG8_SA(0, 0), a2, voffA);
;             PG8_WAIT_V(8); PG8_WAIT_L(0); PG8_BAR; PG8_MMA(1, 0, At, B0); PG8_MMA(1, 1, At, B1); PG8_BAR; PG8_SCHED;
.LBB0_191:
	s_ashr_i32 s15, s14, 31
	s_lshl_b64 s[16:17], s[14:15], 19
	v_readlane_b32 s18, v235, 31
	v_readlane_b32 s19, v235, 32
	s_add_u32 s16, s18, s16
	s_addc_u32 s17, s19, s17
	s_and_b64 s[18:19], s[0:1], exec
	s_cselect_b32 s15, s17, s23
	s_cselect_b32 s50, s16, s22
	s_ashr_i32 s9, s8, 31
	s_lshl_b64 s[18:19], s[8:9], 19
	s_add_u32 s18, s33, s18
	s_addc_u32 s19, s34, s19
	s_and_b64 s[30:31], s[0:1], exec
	s_cselect_b32 s9, s19, s25
	s_cselect_b32 s51, s18, s24
	s_add_u32 s22, s22, 0x40080
	s_addc_u32 s23, s23, 0
	s_add_u32 s52, s24, 0x100
	s_addc_u32 s53, s25, 0
	s_mov_b32 s54, -2
	ds_read_b128 v[150:153], v147
	ds_read_b128 v[154:157], v147 offset:1024
	ds_read_b128 v[158:161], v147 offset:2048
	ds_read_b128 v[162:165], v147 offset:3072
	ds_read_b128 v[166:169], v148
	ds_read_b128 v[170:173], v148 offset:1024
	ds_read_b128 v[174:177], v148 offset:2048
	ds_read_b128 v[178:181], v148 offset:3072
	s_add_u32 s24, s22, 0xfffc0080
	s_addc_u32 s25, s23, -1
	s_cmp_eq_u32 s54, 12
	s_cselect_b32 s31, s15, s25
	s_cselect_b32 s30, s50, s24
	s_cselect_b32 s25, s9, s53
	s_cselect_b32 s24, s51, s52
	v_lshl_add_u64 v[186:187], s[22:23], 0, v[136:137]
	s_add_i32 m0, s21, 0xc000
	ds_read_b128 v[182:185], v149
	ds_read_b128 v[192:195], v149 offset:1024
	ds_read_b128 v[196:199], v149 offset:2048
	ds_read_b128 v[200:203], v149 offset:3072
	ds_read_b128 v[204:207], v149 offset:4096
	ds_read_b128 v[208:211], v149 offset:5120
	ds_read_b128 v[212:215], v149 offset:6144
	ds_read_b128 v[216:219], v149 offset:7168
	global_load_lds_dwordx4 v[186:187], off
	v_lshl_add_u64 v[186:187], s[22:23], 0, v[138:139]
	s_add_i32 m0, s21, 0xe000
	s_nop 0
	global_load_lds_dwordx4 v[186:187], off
	s_waitcnt vmcnt(8)
	s_waitcnt lgkmcnt(0)
	s_barrier
	s_setprio 1
	v_mfma_f32_16x16x32_bf16 v[124:127], v[150:153], v[182:185], 0
	v_mfma_f32_16x16x32_bf16 v[120:123], v[158:161], v[182:185], 0
	v_mfma_f32_16x16x32_bf16 v[108:111], v[150:153], v[196:199], 0
	v_mfma_f32_16x16x32_bf16 v[104:107], v[158:161], v[196:199], 0
	v_mfma_f32_16x16x32_bf16 v[92:95], v[150:153], v[204:207], 0
	v_mfma_f32_16x16x32_bf16 v[88:91], v[158:161], v[204:207], 0
	v_mfma_f32_16x16x32_bf16 v[76:79], v[150:153], v[212:215], 0
	v_mfma_f32_16x16x32_bf16 v[72:75], v[158:161], v[212:215], 0
	v_mfma_f32_16x16x32_bf16 v[124:127], v[154:157], v[192:195], v[124:127]
	v_mfma_f32_16x16x32_bf16 v[120:123], v[162:165], v[192:195], v[120:123]
	v_mfma_f32_16x16x32_bf16 v[108:111], v[154:157], v[200:203], v[108:111]
	v_mfma_f32_16x16x32_bf16 v[104:107], v[162:165], v[200:203], v[104:107]
	v_mfma_f32_16x16x32_bf16 v[92:95], v[154:157], v[208:211], v[92:95]
	v_mfma_f32_16x16x32_bf16 v[88:91], v[162:165], v[208:211], v[88:91]
	v_mfma_f32_16x16x32_bf16 v[76:79], v[154:157], v[216:219], v[76:79]
	v_mfma_f32_16x16x32_bf16 v[72:75], v[162:165], v[216:219], v[72:75]
	v_mfma_f32_16x16x32_bf16 v[116:119], v[166:169], v[182:185], 0
	v_mfma_f32_16x16x32_bf16 v[112:115], v[174:177], v[182:185], 0
	v_mfma_f32_16x16x32_bf16 v[100:103], v[166:169], v[196:199], 0
	v_mfma_f32_16x16x32_bf16 v[96:99], v[174:177], v[196:199], 0
	v_mfma_f32_16x16x32_bf16 v[84:87], v[166:169], v[204:207], 0
	v_mfma_f32_16x16x32_bf16 v[80:83], v[174:177], v[204:207], 0
	v_mfma_f32_16x16x32_bf16 v[68:71], v[166:169], v[212:215], 0
	v_mfma_f32_16x16x32_bf16 v[64:67], v[174:177], v[212:215], 0
	v_mfma_f32_16x16x32_bf16 v[116:119], v[170:173], v[192:195], v[116:119]
	v_mfma_f32_16x16x32_bf16 v[112:115], v[178:181], v[192:195], v[112:115]
	v_mfma_f32_16x16x32_bf16 v[100:103], v[170:173], v[200:203], v[100:103]
	v_mfma_f32_16x16x32_bf16 v[96:99], v[178:181], v[200:203], v[96:99]
	v_mfma_f32_16x16x32_bf16 v[84:87], v[170:173], v[208:211], v[84:87]
	v_mfma_f32_16x16x32_bf16 v[80:83], v[178:181], v[208:211], v[80:83]
	v_mfma_f32_16x16x32_bf16 v[68:71], v[170:173], v[216:219], v[68:71]
	v_mfma_f32_16x16x32_bf16 v[64:67], v[178:181], v[216:219], v[64:67]
	s_setprio 0
	s_barrier
	s_add_i32 s55, s46, s35
	v_lshl_add_u64 v[186:187], s[24:25], 0, v[132:133]
	s_mov_b32 m0, s55
	ds_read_b128 v[182:185], v149 offset:16384
	ds_read_b128 v[192:195], v149 offset:17408
	ds_read_b128 v[196:199], v149 offset:18432
	ds_read_b128 v[200:203], v149 offset:19456
	ds_read_b128 v[204:207], v149 offset:20480
	ds_read_b128 v[208:211], v149 offset:21504
	ds_read_b128 v[212:215], v149 offset:22528
	ds_read_b128 v[216:219], v149 offset:23552
	global_load_lds_dwordx4 v[186:187], off
	s_add_i32 m0, s55, 0x2000
	s_add_u32 s56, s24, 0x40000
	v_lshl_add_u64 v[220:221], s[24:25], 0, v[128:129]
	s_addc_u32 s57, s25, 0
	s_add_i32 s55, s47, s35
	global_load_lds_dwordx4 v[220:221], off
	v_lshl_add_u64 v[222:223], s[56:57], 0, v[132:133]
	s_mov_b32 m0, s55
	v_lshl_add_u64 v[224:225], s[30:31], 0, v[130:131]
	global_load_lds_dwordx4 v[222:223], off
	v_lshl_add_u64 v[222:223], s[56:57], 0, v[128:129]
	s_add_i32 m0, s55, 0x2000
	s_nop 0
	global_load_lds_dwordx4 v[222:223], off
	v_lshl_add_u64 v[222:223], s[30:31], 0, v[134:135]
	s_mov_b32 m0, s21
	s_nop 0
	global_load_lds_dwordx4 v[222:223], off
	s_mov_b32 m0, s38
	s_nop 0
	global_load_lds_dwordx4 v[224:225], off
	s_waitcnt vmcnt(8)
	s_waitcnt lgkmcnt(0)
	s_barrier
; #define PG8_STAGE(bufoff, gbase, voff) do { _Pragma("unroll") for (int _i = 0; _i < 2; ++_i) \
;         __builtin_amdgcn_global_load_lds((const unsigned*)((const char*)(gbase) + (voff)[_i]), (PG8_LAS unsigned*)(lds + (bufoff) + ldsw + _i * 8192), 16, 0, 0); } while (0)
; #define PG8_LDA(dst, b, h) do { _Pragma("unroll") for (int m = 0; m < 4; ++m) _Pragma("unroll") for (int k = 0; k < 2; ++k) dst[m][k] = *(const PG8_LAS bf16x8*)(lds + PG8_SA(b, h) + aoff + m * 2048 + k * 1024); } while (0)
; #define PG8_LDB(dst, b, h) do { _Pragma("unroll") for (int n = 0; n < 2; ++n) _Pragma("unroll") for (int k = 0; k < 2; ++k) dst[n][k] = *(const PG8_LAS bf16x8*)(lds + PG8_SB(b, h) + boff + n * 2048 + k * 1024); } while (0)
; #define PG8_MMA(ai, bj, At, Bt) do { __builtin_amdgcn_s_setprio(1); _Pragma("unroll") for (int m = 0; m < 4; ++m) _Pragma("unroll") for (int n = 0; n < 2; ++n) _Pragma("unroll") for (int k = 0; k < 2; ++k) \
;         acc[ai][bj][m][n] = __builtin_amdgcn_mfma_f32_16x16x32_bf16(Bt[n][k], At[m][k], acc[ai][bj][m][n], 0, 0, 0); __builtin_amdgcn_s_setprio(0); } while (0)
; #define PG8_WAIT_V(n) asm volatile("s_waitcnt vmcnt(" #n ")" ::: "memory")
; #define PG8_WAIT_L(n) asm volatile("s_waitcnt lgkmcnt(" #n ")" ::: "memory")
; #define PG8_BAR __builtin_amdgcn_s_barrier()
; #define PG8_SCHED __builtin_amdgcn_sched_barrier(0)
; template <class Epi, class Sched, bool ALIGN_EPI = false, bool SP2 = false>
; __device__ __forceinline__ void gemm_phase(PG8_LAS unsigned char* lds, const Gemm g, const Sched& S, const Epi& E) {
;     ...
;             PG8_WAIT_V(8); PG8_WAIT_L(0); PG8_BAR; PG8_MMA(1, 0, At, B0); PG8_MMA(1, 1, At, B1); PG8_BAR; PG8_SCHED;
;             PG8_LDB(B0, 1, 0); PG8_LDB(B1, 1, 1); PG8_SCHED; PG8_LDA(At, 1, 0); PG8_STAGE(PG8_SA(0, 1), a2 + hstep, voffA);
;             PG8_WAIT_V(8); PG8_WAIT_L(0); PG8_BAR; PG8_MMA(0, 0, At, B0); PG8_MMA(0, 1, At, B1); PG8_BAR; PG8_SCHED;
	s_setprio 1
	v_mfma_f32_16x16x32_bf16 v[60:63], v[150:153], v[182:185], 0
	v_mfma_f32_16x16x32_bf16 v[56:59], v[158:161], v[182:185], 0
	v_mfma_f32_16x16x32_bf16 v[44:47], v[150:153], v[196:199], 0
	v_mfma_f32_16x16x32_bf16 v[40:43], v[158:161], v[196:199], 0
	v_mfma_f32_16x16x32_bf16 v[28:31], v[150:153], v[204:207], 0
	v_mfma_f32_16x16x32_bf16 v[24:27], v[158:161], v[204:207], 0
	v_mfma_f32_16x16x32_bf16 v[12:15], v[150:153], v[212:215], 0
	v_mfma_f32_16x16x32_bf16 v[8:11], v[158:161], v[212:215], 0
	v_mfma_f32_16x16x32_bf16 v[60:63], v[154:157], v[192:195], v[60:63]
	v_mfma_f32_16x16x32_bf16 v[56:59], v[162:165], v[192:195], v[56:59]
	v_mfma_f32_16x16x32_bf16 v[44:47], v[154:157], v[200:203], v[44:47]
	v_mfma_f32_16x16x32_bf16 v[40:43], v[162:165], v[200:203], v[40:43]
	v_mfma_f32_16x16x32_bf16 v[28:31], v[154:157], v[208:211], v[28:31]
	v_mfma_f32_16x16x32_bf16 v[24:27], v[162:165], v[208:211], v[24:27]
	v_mfma_f32_16x16x32_bf16 v[12:15], v[154:157], v[216:219], v[12:15]
	v_mfma_f32_16x16x32_bf16 v[8:11], v[162:165], v[216:219], v[8:11]
	v_mfma_f32_16x16x32_bf16 v[52:55], v[166:169], v[182:185], 0
	v_mfma_f32_16x16x32_bf16 v[48:51], v[174:177], v[182:185], 0
	v_mfma_f32_16x16x32_bf16 v[36:39], v[166:169], v[196:199], 0
	v_mfma_f32_16x16x32_bf16 v[32:35], v[174:177], v[196:199], 0
	v_mfma_f32_16x16x32_bf16 v[20:23], v[166:169], v[204:207], 0
	v_mfma_f32_16x16x32_bf16 v[16:19], v[174:177], v[204:207], 0
	v_mfma_f32_16x16x32_bf16 v[4:7], v[166:169], v[212:215], 0
	v_mfma_f32_16x16x32_bf16 v[0:3], v[174:177], v[212:215], 0
	v_mfma_f32_16x16x32_bf16 v[52:55], v[170:173], v[192:195], v[52:55]
	v_mfma_f32_16x16x32_bf16 v[48:51], v[178:181], v[192:195], v[48:51]
	v_mfma_f32_16x16x32_bf16 v[36:39], v[170:173], v[200:203], v[36:39]
	v_mfma_f32_16x16x32_bf16 v[32:35], v[178:181], v[200:203], v[32:35]
	v_mfma_f32_16x16x32_bf16 v[20:23], v[170:173], v[208:211], v[20:23]
	v_mfma_f32_16x16x32_bf16 v[16:19], v[178:181], v[208:211], v[16:19]
	v_mfma_f32_16x16x32_bf16 v[4:7], v[170:173], v[216:219], v[4:7]
	v_mfma_f32_16x16x32_bf16 v[0:3], v[178:181], v[216:219], v[0:3]
	s_setprio 0
	s_barrier
	s_add_i32 s55, 0, 0x18000
	s_add_i32 s56, 0, 0x1c000
	v_add_u32_e32 v162, s55, v145
	v_add_u32_e32 v178, s56, v145
	ds_read_b128 v[150:153], v162
	ds_read_b128 v[154:157], v162 offset:1024
	ds_read_b128 v[158:161], v162 offset:2048
	ds_read_b128 v[162:165], v162 offset:3072
	ds_read_b128 v[166:169], v178
	ds_read_b128 v[170:173], v178 offset:1024
	ds_read_b128 v[174:177], v178 offset:2048
	ds_read_b128 v[178:181], v178 offset:3072
	s_add_u32 s30, s30, 0x40000
	s_addc_u32 s31, s31, 0
	s_mov_b32 m0, s39
	v_lshl_add_u64 v[226:227], s[30:31], 0, v[134:135]
	ds_read_b128 v[182:185], v149 offset:32768
	ds_read_b128 v[192:195], v149 offset:33792
	ds_read_b128 v[196:199], v149 offset:34816
	ds_read_b128 v[200:203], v149 offset:35840
	ds_read_b128 v[204:207], v149 offset:36864
	ds_read_b128 v[208:211], v149 offset:37888
	ds_read_b128 v[212:215], v149 offset:38912
	ds_read_b128 v[216:219], v149 offset:39936
	global_load_lds_dwordx4 v[226:227], off
	v_lshl_add_u64 v[226:227], s[30:31], 0, v[130:131]
	s_mov_b32 m0, s40
	s_nop 0
	global_load_lds_dwordx4 v[226:227], off
	s_waitcnt vmcnt(8)
	s_waitcnt lgkmcnt(0)
	s_barrier
	s_setprio 1
	v_mfma_f32_16x16x32_bf16 v[124:127], v[150:153], v[182:185], v[124:127]
	v_mfma_f32_16x16x32_bf16 v[120:123], v[158:161], v[182:185], v[120:123]
	v_mfma_f32_16x16x32_bf16 v[108:111], v[150:153], v[196:199], v[108:111]
	v_mfma_f32_16x16x32_bf16 v[104:107], v[158:161], v[196:199], v[104:107]
	v_mfma_f32_16x16x32_bf16 v[92:95], v[150:153], v[204:207], v[92:95]
	v_mfma_f32_16x16x32_bf16 v[88:91], v[158:161], v[204:207], v[88:91]
	v_mfma_f32_16x16x32_bf16 v[76:79], v[150:153], v[212:215], v[76:79]
	v_mfma_f32_16x16x32_bf16 v[72:75], v[158:161], v[212:215], v[72:75]
	v_mfma_f32_16x16x32_bf16 v[124:127], v[154:157], v[192:195], v[124:127]
	v_mfma_f32_16x16x32_bf16 v[120:123], v[162:165], v[192:195], v[120:123]
	v_mfma_f32_16x16x32_bf16 v[108:111], v[154:157], v[200:203], v[108:111]
	v_mfma_f32_16x16x32_bf16 v[104:107], v[162:165], v[200:203], v[104:107]
	v_mfma_f32_16x16x32_bf16 v[92:95], v[154:157], v[208:211], v[92:95]
	v_mfma_f32_16x16x32_bf16 v[88:91], v[162:165], v[208:211], v[88:91]
	v_mfma_f32_16x16x32_bf16 v[76:79], v[154:157], v[216:219], v[76:79]
	v_mfma_f32_16x16x32_bf16 v[72:75], v[162:165], v[216:219], v[72:75]
	v_mfma_f32_16x16x32_bf16 v[116:119], v[166:169], v[182:185], v[116:119]
	v_mfma_f32_16x16x32_bf16 v[112:115], v[174:177], v[182:185], v[112:115]
	v_mfma_f32_16x16x32_bf16 v[100:103], v[166:169], v[196:199], v[100:103]
	v_mfma_f32_16x16x32_bf16 v[96:99], v[174:177], v[196:199], v[96:99]
	v_mfma_f32_16x16x32_bf16 v[84:87], v[166:169], v[204:207], v[84:87]
	v_mfma_f32_16x16x32_bf16 v[80:83], v[174:177], v[204:207], v[80:83]
	v_mfma_f32_16x16x32_bf16 v[68:71], v[166:169], v[212:215], v[68:71]
	v_mfma_f32_16x16x32_bf16 v[64:67], v[174:177], v[212:215], v[64:67]
	v_mfma_f32_16x16x32_bf16 v[116:119], v[170:173], v[192:195], v[116:119]
	v_mfma_f32_16x16x32_bf16 v[112:115], v[178:181], v[192:195], v[112:115]
	v_mfma_f32_16x16x32_bf16 v[100:103], v[170:173], v[200:203], v[100:103]
	v_mfma_f32_16x16x32_bf16 v[96:99], v[178:181], v[200:203], v[96:99]
	v_mfma_f32_16x16x32_bf16 v[84:87], v[170:173], v[208:211], v[84:87]
	v_mfma_f32_16x16x32_bf16 v[80:83], v[178:181], v[208:211], v[80:83]
	v_mfma_f32_16x16x32_bf16 v[68:71], v[170:173], v[216:219], v[68:71]
	v_mfma_f32_16x16x32_bf16 v[64:67], v[178:181], v[216:219], v[64:67]
	s_setprio 0
	s_barrier
; #define PG8_STAGE(bufoff, gbase, voff) do { _Pragma("unroll") for (int _i = 0; _i < 2; ++_i) \
;         __builtin_amdgcn_global_load_lds((const unsigned*)((const char*)(gbase) + (voff)[_i]), (PG8_LAS unsigned*)(lds + (bufoff) + ldsw + _i * 8192), 16, 0, 0); } while (0)
; #define PG8_LDA(dst, b, h) do { _Pragma("unroll") for (int m = 0; m < 4; ++m) _Pragma("unroll") for (int k = 0; k < 2; ++k) dst[m][k] = *(const PG8_LAS bf16x8*)(lds + PG8_SA(b, h) + aoff + m * 2048 + k * 1024); } while (0)
; #define PG8_MMA(ai, bj, At, Bt) do { __builtin_amdgcn_s_setprio(1); _Pragma("unroll") for (int m = 0; m < 4; ++m) _Pragma("unroll") for (int n = 0; n < 2; ++n) _Pragma("unroll") for (int k = 0; k < 2; ++k) \
;         acc[ai][bj][m][n] = __builtin_amdgcn_mfma_f32_16x16x32_bf16(Bt[n][k], At[m][k], acc[ai][bj][m][n], 0, 0, 0); __builtin_amdgcn_s_setprio(0); } while (0)
; #define PG8_WAIT_V(n) asm volatile("s_waitcnt vmcnt(" #n ")" ::: "memory")
; #define PG8_WAIT_L(n) asm volatile("s_waitcnt lgkmcnt(" #n ")" ::: "memory")
; #define PG8_BAR __builtin_amdgcn_s_barrier()
; #define PG8_SCHED __builtin_amdgcn_sched_barrier(0)
; template <class Epi, class Sched, bool ALIGN_EPI = false, bool SP2 = false>
; __device__ __forceinline__ void gemm_phase(PG8_LAS unsigned char* lds, const Gemm g, const Sched& S, const Epi& E) {
;     ...
;         for (int t = 0; t < nt; t += 2) {
;             const bool last = (t == nt - 2);
;             const char* a1 = cA + (size_t)(t + 1) * kstep;
;             const char* a2 = last ? nA : cA + (size_t)(t + 2) * kstep; const char* b2 = last ? nB : cB + (size_t)(t + 2) * kstep;
;     ...
;             PG8_LDA(At, 1, 1); PG8_STAGE(PG8_SB(1, 0), b3, voffB); PG8_STAGE(PG8_SB(1, 1), b3 + hstep, voffB); PG8_STAGE(PG8_SA(1, 0), a3, voffA);
;             PG8_WAIT_V(8); PG8_WAIT_L(0); PG8_BAR; PG8_MMA(1, 0, At, B0); PG8_MMA(1, 1, At, B1); PG8_BAR; PG8_SCHED;
	s_add_i32 s30, s55, s35
	v_lshl_add_u64 v[186:187], v[186:187], 0, s[4:5]
	s_mov_b32 m0, s30
	ds_read_b128 v[182:185], v149 offset:49152
	ds_read_b128 v[192:195], v149 offset:50176
	ds_read_b128 v[196:199], v149 offset:51200
	ds_read_b128 v[200:203], v149 offset:52224
	ds_read_b128 v[204:207], v149 offset:53248
	ds_read_b128 v[208:211], v149 offset:54272
	ds_read_b128 v[212:215], v149 offset:55296
	ds_read_b128 v[216:219], v149 offset:56320
	global_load_lds_dwordx4 v[186:187], off
	s_add_i32 m0, s30, 0x2000
	s_add_u32 s24, s24, 0x40080
	v_lshl_add_u64 v[186:187], v[220:221], 0, s[4:5]
	s_addc_u32 s25, s25, 0
	s_add_i32 s30, s56, s35
	global_load_lds_dwordx4 v[186:187], off
	v_lshl_add_u64 v[186:187], s[24:25], 0, v[132:133]
	s_mov_b32 m0, s30
	s_nop 0
	global_load_lds_dwordx4 v[186:187], off
	v_lshl_add_u64 v[186:187], s[24:25], 0, v[128:129]
	s_add_i32 m0, s30, 0x2000
	s_nop 0
	global_load_lds_dwordx4 v[186:187], off
	v_lshl_add_u64 v[186:187], v[222:223], 0, s[4:5]
	s_mov_b32 m0, s42
	s_nop 0
	global_load_lds_dwordx4 v[186:187], off
	v_lshl_add_u64 v[186:187], v[224:225], 0, s[4:5]
	s_mov_b32 m0, s43
	s_nop 0
	global_load_lds_dwordx4 v[186:187], off
	s_waitcnt vmcnt(8)
	s_waitcnt lgkmcnt(0)
	s_barrier
	s_setprio 1
	v_mfma_f32_16x16x32_bf16 v[60:63], v[150:153], v[182:185], v[60:63]
	v_mfma_f32_16x16x32_bf16 v[56:59], v[158:161], v[182:185], v[56:59]
	v_mfma_f32_16x16x32_bf16 v[44:47], v[150:153], v[196:199], v[44:47]
	v_mfma_f32_16x16x32_bf16 v[40:43], v[158:161], v[196:199], v[40:43]
	v_mfma_f32_16x16x32_bf16 v[28:31], v[150:153], v[204:207], v[28:31]
	v_mfma_f32_16x16x32_bf16 v[24:27], v[158:161], v[204:207], v[24:27]
	v_mfma_f32_16x16x32_bf16 v[12:15], v[150:153], v[212:215], v[12:15]
	v_mfma_f32_16x16x32_bf16 v[8:11], v[158:161], v[212:215], v[8:11]
	v_mfma_f32_16x16x32_bf16 v[60:63], v[154:157], v[192:195], v[60:63]
	v_mfma_f32_16x16x32_bf16 v[56:59], v[162:165], v[192:195], v[56:59]
	v_mfma_f32_16x16x32_bf16 v[44:47], v[154:157], v[200:203], v[44:47]
	v_mfma_f32_16x16x32_bf16 v[40:43], v[162:165], v[200:203], v[40:43]
	v_mfma_f32_16x16x32_bf16 v[28:31], v[154:157], v[208:211], v[28:31]
	v_mfma_f32_16x16x32_bf16 v[24:27], v[162:165], v[208:211], v[24:27]
	v_mfma_f32_16x16x32_bf16 v[12:15], v[154:157], v[216:219], v[12:15]
	v_mfma_f32_16x16x32_bf16 v[8:11], v[162:165], v[216:219], v[8:11]
	v_mfma_f32_16x16x32_bf16 v[52:55], v[166:169], v[182:185], v[52:55]
	v_mfma_f32_16x16x32_bf16 v[48:51], v[174:177], v[182:185], v[48:51]
	v_mfma_f32_16x16x32_bf16 v[36:39], v[166:169], v[196:199], v[36:39]
	v_mfma_f32_16x16x32_bf16 v[32:35], v[174:177], v[196:199], v[32:35]
	v_mfma_f32_16x16x32_bf16 v[20:23], v[166:169], v[204:207], v[20:23]
	v_mfma_f32_16x16x32_bf16 v[16:19], v[174:177], v[204:207], v[16:19]
	v_mfma_f32_16x16x32_bf16 v[4:7], v[166:169], v[212:215], v[4:7]
	v_mfma_f32_16x16x32_bf16 v[0:3], v[174:177], v[212:215], v[0:3]
	v_mfma_f32_16x16x32_bf16 v[52:55], v[170:173], v[192:195], v[52:55]
	v_mfma_f32_16x16x32_bf16 v[48:51], v[178:181], v[192:195], v[48:51]
	v_mfma_f32_16x16x32_bf16 v[36:39], v[170:173], v[200:203], v[36:39]
	v_mfma_f32_16x16x32_bf16 v[32:35], v[178:181], v[200:203], v[32:35]
	v_mfma_f32_16x16x32_bf16 v[20:23], v[170:173], v[208:211], v[20:23]
	v_mfma_f32_16x16x32_bf16 v[16:19], v[178:181], v[208:211], v[16:19]
	v_mfma_f32_16x16x32_bf16 v[4:7], v[170:173], v[216:219], v[4:7]
	v_mfma_f32_16x16x32_bf16 v[0:3], v[178:181], v[216:219], v[0:3]
	s_setprio 0
	s_barrier
	s_add_i32 s54, s54, 2
	s_add_u32 s22, s22, 0x100
	s_addc_u32 s23, s23, 0
	s_add_u32 s52, s52, 0x100
	s_addc_u32 s53, s53, 0

; #define PG8_STAGE(bufoff, gbase, voff) do { _Pragma("unroll") for (int _i = 0; _i < 2; ++_i) \
;         __builtin_amdgcn_global_load_lds((const unsigned*)((const char*)(gbase) + (voff)[_i]), (PG8_LAS unsigned*)(lds + (bufoff) + ldsw + _i * 8192), 16, 0, 0); } while (0)
; #define PG8_LDA(dst, b, h) do { _Pragma("unroll") for (int m = 0; m < 4; ++m) _Pragma("unroll") for (int k = 0; k < 2; ++k) dst[m][k] = *(const PG8_LAS bf16x8*)(lds + PG8_SA(b, h) + aoff + m * 2048 + k * 1024); } while (0)
; #define PG8_LDB(dst, b, h) do { _Pragma("unroll") for (int n = 0; n < 2; ++n) _Pragma("unroll") for (int k = 0; k < 2; ++k) dst[n][k] = *(const PG8_LAS bf16x8*)(lds + PG8_SB(b, h) + boff + n * 2048 + k * 1024); } while (0)
; #define PG8_MMA(ai, bj, At, Bt) do { __builtin_amdgcn_s_setprio(1); _Pragma("unroll") for (int m = 0; m < 4; ++m) _Pragma("unroll") for (int n = 0; n < 2; ++n) _Pragma("unroll") for (int k = 0; k < 2; ++k) \
;         acc[ai][bj][m][n] = __builtin_amdgcn_mfma_f32_16x16x32_bf16(Bt[n][k], At[m][k], acc[ai][bj][m][n], 0, 0, 0); __builtin_amdgcn_s_setprio(0); } while (0)
; #define PG8_WAIT_V(n) asm volatile("s_waitcnt vmcnt(" #n ")" ::: "memory")
; #define PG8_WAIT_L(n) asm volatile("s_waitcnt lgkmcnt(" #n ")" ::: "memory")
; #define PG8_BAR __builtin_amdgcn_s_barrier()
; #define PG8_SCHED __builtin_amdgcn_sched_barrier(0)
; template <class Epi, class Sched, bool ALIGN_EPI = false, bool SP2 = false>
; __device__ __forceinline__ void gemm_phase(PG8_LAS unsigned char* lds, const Gemm g, const Sched& S, const Epi& E) {
;     ...
;             PG8_LDB(B0, 0, 0); PG8_LDB(B1, 0, 1); PG8_SCHED; PG8_LDA(At, 0, 0); PG8_STAGE(PG8_SA(1, 1), a1 + hstep, voffA);
;             PG8_WAIT_V(8); PG8_WAIT_L(0); PG8_BAR; PG8_MMA(0, 0, At, B0); PG8_MMA(0, 1, At, B1); PG8_BAR; PG8_SCHED;
;             PG8_LDA(At, 0, 1); PG8_STAGE(PG8_SB(0, 0), b2, voffB); PG8_STAGE(PG8_SB(0, 1), b2 + hstep, voffB); PG8_STAGE(PG8_SA(0, 0), a2, voffA);
;             PG8_WAIT_V(8); PG8_WAIT_L(0); PG8_BAR; PG8_MMA(1, 0, At, B0); PG8_MMA(1, 1, At, B1); PG8_BAR; PG8_SCHED;
.LBB0_273:
	s_add_u32 s58, s34, 0x100
	s_addc_u32 s59, s35, 0
	s_mov_b32 s60, -2
	s_waitcnt lgkmcnt(0)
	ds_read_b128 v[128:131], v161
	ds_read_b128 v[132:135], v161 offset:1024
	ds_read_b128 v[152:155], v161 offset:2048
	ds_read_b128 v[166:169], v161 offset:3072
	ds_read_b128 v[170:173], v162
	ds_read_b128 v[174:177], v162 offset:1024
	ds_read_b128 v[178:181], v162 offset:2048
	ds_read_b128 v[182:185], v162 offset:3072
	s_add_u32 s34, s8, 0x100
	s_addc_u32 s35, s9, 0
	s_cmp_eq_u32 s60, 40
	s_cselect_b32 s39, s1, s35
	s_cselect_b32 s38, s0, s34
	s_cselect_b32 s37, s31, s59
	s_cselect_b32 s36, s30, s58
	v_lshl_add_u64 v[156:157], s[8:9], 0, v[144:145]
	s_add_i32 m0, s42, 0xc000
	ds_read_b128 v[192:195], v163
	ds_read_b128 v[196:199], v163 offset:1024
	ds_read_b128 v[200:203], v163 offset:2048
	ds_read_b128 v[204:207], v163 offset:3072
	ds_read_b128 v[208:211], v163 offset:4096
	ds_read_b128 v[212:215], v163 offset:5120
	ds_read_b128 v[216:219], v163 offset:6144
	ds_read_b128 v[220:223], v163 offset:7168
	global_load_lds_dwordx4 v[156:157], off
	v_lshl_add_u64 v[156:157], s[8:9], 0, v[146:147]
	s_add_i32 m0, s42, 0xe000
	s_nop 0
	global_load_lds_dwordx4 v[156:157], off
	s_waitcnt vmcnt(8)
	s_waitcnt lgkmcnt(0)
	s_barrier
	s_setprio 1
	v_mfma_f32_16x16x32_bf16 v[124:127], v[128:131], v[192:195], 0
	v_mfma_f32_16x16x32_bf16 v[120:123], v[152:155], v[192:195], 0
	v_mfma_f32_16x16x32_bf16 v[108:111], v[128:131], v[200:203], 0
	v_mfma_f32_16x16x32_bf16 v[104:107], v[152:155], v[200:203], 0
	v_mfma_f32_16x16x32_bf16 v[92:95], v[128:131], v[208:211], 0
	v_mfma_f32_16x16x32_bf16 v[88:91], v[152:155], v[208:211], 0
	v_mfma_f32_16x16x32_bf16 v[76:79], v[128:131], v[216:219], 0
	v_mfma_f32_16x16x32_bf16 v[72:75], v[152:155], v[216:219], 0
	v_mfma_f32_16x16x32_bf16 v[124:127], v[132:135], v[196:199], v[124:127]
	v_mfma_f32_16x16x32_bf16 v[120:123], v[166:169], v[196:199], v[120:123]
	v_mfma_f32_16x16x32_bf16 v[108:111], v[132:135], v[204:207], v[108:111]
	v_mfma_f32_16x16x32_bf16 v[104:107], v[166:169], v[204:207], v[104:107]
	v_mfma_f32_16x16x32_bf16 v[92:95], v[132:135], v[212:215], v[92:95]
	v_mfma_f32_16x16x32_bf16 v[88:91], v[166:169], v[212:215], v[88:91]
	v_mfma_f32_16x16x32_bf16 v[76:79], v[132:135], v[220:223], v[76:79]
	v_mfma_f32_16x16x32_bf16 v[72:75], v[166:169], v[220:223], v[72:75]
	v_mfma_f32_16x16x32_bf16 v[116:119], v[170:173], v[192:195], 0
	v_mfma_f32_16x16x32_bf16 v[112:115], v[178:181], v[192:195], 0
	v_mfma_f32_16x16x32_bf16 v[100:103], v[170:173], v[200:203], 0
	v_mfma_f32_16x16x32_bf16 v[96:99], v[178:181], v[200:203], 0
	v_mfma_f32_16x16x32_bf16 v[84:87], v[170:173], v[208:211], 0
	v_mfma_f32_16x16x32_bf16 v[80:83], v[178:181], v[208:211], 0
	v_mfma_f32_16x16x32_bf16 v[68:71], v[170:173], v[216:219], 0
	v_mfma_f32_16x16x32_bf16 v[64:67], v[178:181], v[216:219], 0
	v_mfma_f32_16x16x32_bf16 v[116:119], v[174:177], v[196:199], v[116:119]
	v_mfma_f32_16x16x32_bf16 v[112:115], v[182:185], v[196:199], v[112:115]
	v_mfma_f32_16x16x32_bf16 v[100:103], v[174:177], v[204:207], v[100:103]
	v_mfma_f32_16x16x32_bf16 v[96:99], v[182:185], v[204:207], v[96:99]
	v_mfma_f32_16x16x32_bf16 v[84:87], v[174:177], v[212:215], v[84:87]
	v_mfma_f32_16x16x32_bf16 v[80:83], v[182:185], v[212:215], v[80:83]
	v_mfma_f32_16x16x32_bf16 v[68:71], v[174:177], v[220:223], v[68:71]
	v_mfma_f32_16x16x32_bf16 v[64:67], v[182:185], v[220:223], v[64:67]
	s_setprio 0
	s_barrier
	s_add_i32 s8, s52, s41
	v_lshl_add_u64 v[156:157], s[36:37], 0, v[138:139]
	s_mov_b32 m0, s8
	ds_read_b128 v[192:195], v163 offset:16384
	ds_read_b128 v[196:199], v163 offset:17408
	ds_read_b128 v[200:203], v163 offset:18432
	ds_read_b128 v[204:207], v163 offset:19456
	ds_read_b128 v[208:211], v163 offset:20480
	ds_read_b128 v[212:215], v163 offset:21504
	ds_read_b128 v[216:219], v163 offset:22528
	ds_read_b128 v[220:223], v163 offset:23552
	global_load_lds_dwordx4 v[156:157], off
	s_add_i32 m0, s8, 0x2000
	s_add_u32 s8, s36, 0xb0000
	v_lshl_add_u64 v[186:187], s[36:37], 0, v[142:143]
	s_addc_u32 s9, s37, 0
	s_add_i32 s61, s53, s41
	global_load_lds_dwordx4 v[186:187], off
	v_lshl_add_u64 v[224:225], s[8:9], 0, v[138:139]
	s_mov_b32 m0, s61
	v_lshl_add_u64 v[226:227], s[38:39], 0, v[140:141]
	global_load_lds_dwordx4 v[224:225], off
	v_lshl_add_u64 v[224:225], s[8:9], 0, v[142:143]
	s_add_i32 m0, s61, 0x2000
	s_nop 0
	global_load_lds_dwordx4 v[224:225], off
	v_lshl_add_u64 v[224:225], s[38:39], 0, v[136:137]
	s_mov_b32 m0, s42
	s_nop 0
	global_load_lds_dwordx4 v[224:225], off
	s_mov_b32 m0, s43
	s_nop 0
	global_load_lds_dwordx4 v[226:227], off
	s_waitcnt vmcnt(8)
	s_waitcnt lgkmcnt(0)
	s_barrier
; #define PG8_STAGE(bufoff, gbase, voff) do { _Pragma("unroll") for (int _i = 0; _i < 2; ++_i) \
;         __builtin_amdgcn_global_load_lds((const unsigned*)((const char*)(gbase) + (voff)[_i]), (PG8_LAS unsigned*)(lds + (bufoff) + ldsw + _i * 8192), 16, 0, 0); } while (0)
; #define PG8_LDA(dst, b, h) do { _Pragma("unroll") for (int m = 0; m < 4; ++m) _Pragma("unroll") for (int k = 0; k < 2; ++k) dst[m][k] = *(const PG8_LAS bf16x8*)(lds + PG8_SA(b, h) + aoff + m * 2048 + k * 1024); } while (0)
; #define PG8_LDB(dst, b, h) do { _Pragma("unroll") for (int n = 0; n < 2; ++n) _Pragma("unroll") for (int k = 0; k < 2; ++k) dst[n][k] = *(const PG8_LAS bf16x8*)(lds + PG8_SB(b, h) + boff + n * 2048 + k * 1024); } while (0)
; #define PG8_MMA(ai, bj, At, Bt) do { __builtin_amdgcn_s_setprio(1); _Pragma("unroll") for (int m = 0; m < 4; ++m) _Pragma("unroll") for (int n = 0; n < 2; ++n) _Pragma("unroll") for (int k = 0; k < 2; ++k) \
;         acc[ai][bj][m][n] = __builtin_amdgcn_mfma_f32_16x16x32_bf16(Bt[n][k], At[m][k], acc[ai][bj][m][n], 0, 0, 0); __builtin_amdgcn_s_setprio(0); } while (0)
; #define PG8_WAIT_V(n) asm volatile("s_waitcnt vmcnt(" #n ")" ::: "memory")
; #define PG8_WAIT_L(n) asm volatile("s_waitcnt lgkmcnt(" #n ")" ::: "memory")
; #define PG8_BAR __builtin_amdgcn_s_barrier()
; #define PG8_SCHED __builtin_amdgcn_sched_barrier(0)
; template <class Epi, class Sched, bool ALIGN_EPI = false, bool SP2 = false>
; __device__ __forceinline__ void gemm_phase(PG8_LAS unsigned char* lds, const Gemm g, const Sched& S, const Epi& E) {
;     ...
;             PG8_WAIT_V(8); PG8_WAIT_L(0); PG8_BAR; PG8_MMA(1, 0, At, B0); PG8_MMA(1, 1, At, B1); PG8_BAR; PG8_SCHED;
;             PG8_LDB(B0, 1, 0); PG8_LDB(B1, 1, 1); PG8_SCHED; PG8_LDA(At, 1, 0); PG8_STAGE(PG8_SA(0, 1), a2 + hstep, voffA);
;             PG8_WAIT_V(8); PG8_WAIT_L(0); PG8_BAR; PG8_MMA(0, 0, At, B0); PG8_MMA(0, 1, At, B1); PG8_BAR; PG8_SCHED;
	s_setprio 1
	v_mfma_f32_16x16x32_bf16 v[60:63], v[128:131], v[192:195], 0
	v_mfma_f32_16x16x32_bf16 v[56:59], v[152:155], v[192:195], 0
	v_mfma_f32_16x16x32_bf16 v[44:47], v[128:131], v[200:203], 0
	v_mfma_f32_16x16x32_bf16 v[40:43], v[152:155], v[200:203], 0
	v_mfma_f32_16x16x32_bf16 v[28:31], v[128:131], v[208:211], 0
	v_mfma_f32_16x16x32_bf16 v[24:27], v[152:155], v[208:211], 0
	v_mfma_f32_16x16x32_bf16 v[12:15], v[128:131], v[216:219], 0
	v_mfma_f32_16x16x32_bf16 v[8:11], v[152:155], v[216:219], 0
	v_mfma_f32_16x16x32_bf16 v[60:63], v[132:135], v[196:199], v[60:63]
	v_mfma_f32_16x16x32_bf16 v[56:59], v[166:169], v[196:199], v[56:59]
	v_mfma_f32_16x16x32_bf16 v[44:47], v[132:135], v[204:207], v[44:47]
	v_mfma_f32_16x16x32_bf16 v[40:43], v[166:169], v[204:207], v[40:43]
	v_mfma_f32_16x16x32_bf16 v[28:31], v[132:135], v[212:215], v[28:31]
	v_mfma_f32_16x16x32_bf16 v[24:27], v[166:169], v[212:215], v[24:27]
	v_mfma_f32_16x16x32_bf16 v[12:15], v[132:135], v[220:223], v[12:15]
	v_mfma_f32_16x16x32_bf16 v[8:11], v[166:169], v[220:223], v[8:11]
	v_mfma_f32_16x16x32_bf16 v[52:55], v[170:173], v[192:195], 0
	v_mfma_f32_16x16x32_bf16 v[48:51], v[178:181], v[192:195], 0
	v_mfma_f32_16x16x32_bf16 v[36:39], v[170:173], v[200:203], 0
	v_mfma_f32_16x16x32_bf16 v[32:35], v[178:181], v[200:203], 0
	v_mfma_f32_16x16x32_bf16 v[20:23], v[170:173], v[208:211], 0
	v_mfma_f32_16x16x32_bf16 v[16:19], v[178:181], v[208:211], 0
	v_mfma_f32_16x16x32_bf16 v[4:7], v[170:173], v[216:219], 0
	v_mfma_f32_16x16x32_bf16 v[0:3], v[178:181], v[216:219], 0
	v_mfma_f32_16x16x32_bf16 v[52:55], v[174:177], v[196:199], v[52:55]
	v_mfma_f32_16x16x32_bf16 v[48:51], v[182:185], v[196:199], v[48:51]
	v_mfma_f32_16x16x32_bf16 v[36:39], v[174:177], v[204:207], v[36:39]
	v_mfma_f32_16x16x32_bf16 v[32:35], v[182:185], v[204:207], v[32:35]
	v_mfma_f32_16x16x32_bf16 v[20:23], v[174:177], v[212:215], v[20:23]
	v_mfma_f32_16x16x32_bf16 v[16:19], v[182:185], v[212:215], v[16:19]
	v_mfma_f32_16x16x32_bf16 v[4:7], v[174:177], v[220:223], v[4:7]
	v_mfma_f32_16x16x32_bf16 v[0:3], v[182:185], v[220:223], v[0:3]
	s_setprio 0
	s_barrier
	s_add_i32 s61, 0, 0x18000
	v_add_u32_e32 v165, s61, v159
	s_add_i32 s62, 0, 0x1c000
	ds_read_b128 v[128:131], v165
	ds_read_b128 v[132:135], v165 offset:1024
	ds_read_b128 v[152:155], v165 offset:2048
	ds_read_b128 v[166:169], v165 offset:3072
	v_add_u32_e32 v165, s62, v159
	ds_read_b128 v[170:173], v165
	ds_read_b128 v[174:177], v165 offset:1024
	ds_read_b128 v[178:181], v165 offset:2048
	ds_read_b128 v[182:185], v165 offset:3072
	s_add_u32 s8, s38, 0xb0000
	s_addc_u32 s9, s39, 0
	s_mov_b32 m0, s44
	v_lshl_add_u64 v[228:229], s[8:9], 0, v[136:137]
	ds_read_b128 v[192:195], v163 offset:32768
	ds_read_b128 v[196:199], v163 offset:33792
	ds_read_b128 v[200:203], v163 offset:34816
	ds_read_b128 v[204:207], v163 offset:35840
	ds_read_b128 v[208:211], v163 offset:36864
	ds_read_b128 v[212:215], v163 offset:37888
	ds_read_b128 v[216:219], v163 offset:38912
	ds_read_b128 v[220:223], v163 offset:39936
	global_load_lds_dwordx4 v[228:229], off
	v_lshl_add_u64 v[228:229], s[8:9], 0, v[140:141]
	s_mov_b32 m0, s45
	s_nop 0
	global_load_lds_dwordx4 v[228:229], off
	s_waitcnt vmcnt(8)
	s_waitcnt lgkmcnt(0)
	s_barrier
	s_setprio 1
	v_mfma_f32_16x16x32_bf16 v[124:127], v[128:131], v[192:195], v[124:127]
	v_mfma_f32_16x16x32_bf16 v[120:123], v[152:155], v[192:195], v[120:123]
	v_mfma_f32_16x16x32_bf16 v[108:111], v[128:131], v[200:203], v[108:111]
	v_mfma_f32_16x16x32_bf16 v[104:107], v[152:155], v[200:203], v[104:107]
	v_mfma_f32_16x16x32_bf16 v[92:95], v[128:131], v[208:211], v[92:95]
	v_mfma_f32_16x16x32_bf16 v[88:91], v[152:155], v[208:211], v[88:91]
	v_mfma_f32_16x16x32_bf16 v[76:79], v[128:131], v[216:219], v[76:79]
	v_mfma_f32_16x16x32_bf16 v[72:75], v[152:155], v[216:219], v[72:75]
	v_mfma_f32_16x16x32_bf16 v[124:127], v[132:135], v[196:199], v[124:127]
	v_mfma_f32_16x16x32_bf16 v[120:123], v[166:169], v[196:199], v[120:123]
	v_mfma_f32_16x16x32_bf16 v[108:111], v[132:135], v[204:207], v[108:111]
	v_mfma_f32_16x16x32_bf16 v[104:107], v[166:169], v[204:207], v[104:107]
	v_mfma_f32_16x16x32_bf16 v[92:95], v[132:135], v[212:215], v[92:95]
	v_mfma_f32_16x16x32_bf16 v[88:91], v[166:169], v[212:215], v[88:91]
	v_mfma_f32_16x16x32_bf16 v[76:79], v[132:135], v[220:223], v[76:79]
	v_mfma_f32_16x16x32_bf16 v[72:75], v[166:169], v[220:223], v[72:75]
	v_mfma_f32_16x16x32_bf16 v[116:119], v[170:173], v[192:195], v[116:119]
	v_mfma_f32_16x16x32_bf16 v[112:115], v[178:181], v[192:195], v[112:115]
	v_mfma_f32_16x16x32_bf16 v[100:103], v[170:173], v[200:203], v[100:103]
	v_mfma_f32_16x16x32_bf16 v[96:99], v[178:181], v[200:203], v[96:99]
	v_mfma_f32_16x16x32_bf16 v[84:87], v[170:173], v[208:211], v[84:87]
	v_mfma_f32_16x16x32_bf16 v[80:83], v[178:181], v[208:211], v[80:83]
	v_mfma_f32_16x16x32_bf16 v[68:71], v[170:173], v[216:219], v[68:71]
	v_mfma_f32_16x16x32_bf16 v[64:67], v[178:181], v[216:219], v[64:67]
	v_mfma_f32_16x16x32_bf16 v[116:119], v[174:177], v[196:199], v[116:119]
	v_mfma_f32_16x16x32_bf16 v[112:115], v[182:185], v[196:199], v[112:115]
	v_mfma_f32_16x16x32_bf16 v[100:103], v[174:177], v[204:207], v[100:103]
	v_mfma_f32_16x16x32_bf16 v[96:99], v[182:185], v[204:207], v[96:99]
	v_mfma_f32_16x16x32_bf16 v[84:87], v[174:177], v[212:215], v[84:87]
	v_mfma_f32_16x16x32_bf16 v[80:83], v[182:185], v[212:215], v[80:83]
	v_mfma_f32_16x16x32_bf16 v[68:71], v[174:177], v[220:223], v[68:71]
	v_mfma_f32_16x16x32_bf16 v[64:67], v[182:185], v[220:223], v[64:67]
	s_setprio 0
	s_barrier
; #define PG8_STAGE(bufoff, gbase, voff) do { _Pragma("unroll") for (int _i = 0; _i < 2; ++_i) \
;         __builtin_amdgcn_global_load_lds((const unsigned*)((const char*)(gbase) + (voff)[_i]), (PG8_LAS unsigned*)(lds + (bufoff) + ldsw + _i * 8192), 16, 0, 0); } while (0)
; #define PG8_LDA(dst, b, h) do { _Pragma("unroll") for (int m = 0; m < 4; ++m) _Pragma("unroll") for (int k = 0; k < 2; ++k) dst[m][k] = *(const PG8_LAS bf16x8*)(lds + PG8_SA(b, h) + aoff + m * 2048 + k * 1024); } while (0)
; #define PG8_MMA(ai, bj, At, Bt) do { __builtin_amdgcn_s_setprio(1); _Pragma("unroll") for (int m = 0; m < 4; ++m) _Pragma("unroll") for (int n = 0; n < 2; ++n) _Pragma("unroll") for (int k = 0; k < 2; ++k) \
;         acc[ai][bj][m][n] = __builtin_amdgcn_mfma_f32_16x16x32_bf16(Bt[n][k], At[m][k], acc[ai][bj][m][n], 0, 0, 0); __builtin_amdgcn_s_setprio(0); } while (0)
; #define PG8_WAIT_V(n) asm volatile("s_waitcnt vmcnt(" #n ")" ::: "memory")
; #define PG8_WAIT_L(n) asm volatile("s_waitcnt lgkmcnt(" #n ")" ::: "memory")
; #define PG8_BAR __builtin_amdgcn_s_barrier()
; #define PG8_SCHED __builtin_amdgcn_sched_barrier(0)
; template <class Epi, class Sched, bool ALIGN_EPI = false, bool SP2 = false>
; __device__ __forceinline__ void gemm_phase(PG8_LAS unsigned char* lds, const Gemm g, const Sched& S, const Epi& E) {
;     ...
;         for (int t = 0; t < nt; t += 2) {
;             const bool last = (t == nt - 2);
;             const char* a1 = cA + (size_t)(t + 1) * kstep;
;             const char* a2 = last ? nA : cA + (size_t)(t + 2) * kstep; const char* b2 = last ? nB : cB + (size_t)(t + 2) * kstep;
;     ...
;             PG8_LDA(At, 1, 1); PG8_STAGE(PG8_SB(1, 0), b3, voffB); PG8_STAGE(PG8_SB(1, 1), b3 + hstep, voffB); PG8_STAGE(PG8_SA(1, 0), a3, voffA);
;             PG8_WAIT_V(8); PG8_WAIT_L(0); PG8_BAR; PG8_MMA(1, 0, At, B0); PG8_MMA(1, 1, At, B1); PG8_BAR; PG8_SCHED;
	s_add_i32 s8, s61, s41
	v_lshl_add_u64 v[156:157], v[156:157], 0, s[14:15]
	s_mov_b32 m0, s8
	ds_read_b128 v[192:195], v163 offset:49152
	ds_read_b128 v[196:199], v163 offset:50176
	ds_read_b128 v[200:203], v163 offset:51200
	ds_read_b128 v[204:207], v163 offset:52224
	ds_read_b128 v[208:211], v163 offset:53248
	ds_read_b128 v[212:215], v163 offset:54272
	ds_read_b128 v[216:219], v163 offset:55296
	ds_read_b128 v[220:223], v163 offset:56320
	global_load_lds_dwordx4 v[156:157], off
	s_add_i32 m0, s8, 0x2000
	s_add_u32 s8, s36, 0xb0080
	v_lshl_add_u64 v[156:157], v[186:187], 0, s[14:15]
	s_addc_u32 s9, s37, 0
	s_add_i32 s36, s62, s41
	global_load_lds_dwordx4 v[156:157], off
	v_lshl_add_u64 v[156:157], s[8:9], 0, v[138:139]
	s_mov_b32 m0, s36
	s_nop 0
	global_load_lds_dwordx4 v[156:157], off
	v_lshl_add_u64 v[156:157], s[8:9], 0, v[142:143]
	s_add_i32 m0, s36, 0x2000
	s_nop 0
	global_load_lds_dwordx4 v[156:157], off
	v_lshl_add_u64 v[156:157], v[224:225], 0, s[14:15]
	s_mov_b32 m0, s47
	s_nop 0
	global_load_lds_dwordx4 v[156:157], off
	v_lshl_add_u64 v[156:157], v[226:227], 0, s[14:15]
	s_mov_b32 m0, s48
	s_nop 0
	global_load_lds_dwordx4 v[156:157], off
	s_waitcnt vmcnt(8)
	s_waitcnt lgkmcnt(0)
	s_barrier
	s_setprio 1
	v_mfma_f32_16x16x32_bf16 v[60:63], v[128:131], v[192:195], v[60:63]
	v_mfma_f32_16x16x32_bf16 v[56:59], v[152:155], v[192:195], v[56:59]
	v_mfma_f32_16x16x32_bf16 v[44:47], v[128:131], v[200:203], v[44:47]
	v_mfma_f32_16x16x32_bf16 v[40:43], v[152:155], v[200:203], v[40:43]
	v_mfma_f32_16x16x32_bf16 v[28:31], v[128:131], v[208:211], v[28:31]
	v_mfma_f32_16x16x32_bf16 v[24:27], v[152:155], v[208:211], v[24:27]
	v_mfma_f32_16x16x32_bf16 v[12:15], v[128:131], v[216:219], v[12:15]
	v_mfma_f32_16x16x32_bf16 v[8:11], v[152:155], v[216:219], v[8:11]
	v_mfma_f32_16x16x32_bf16 v[60:63], v[132:135], v[196:199], v[60:63]
	v_mfma_f32_16x16x32_bf16 v[56:59], v[166:169], v[196:199], v[56:59]
	v_mfma_f32_16x16x32_bf16 v[44:47], v[132:135], v[204:207], v[44:47]
	v_mfma_f32_16x16x32_bf16 v[40:43], v[166:169], v[204:207], v[40:43]
	v_mfma_f32_16x16x32_bf16 v[28:31], v[132:135], v[212:215], v[28:31]
	v_mfma_f32_16x16x32_bf16 v[24:27], v[166:169], v[212:215], v[24:27]
	v_mfma_f32_16x16x32_bf16 v[12:15], v[132:135], v[220:223], v[12:15]
	v_mfma_f32_16x16x32_bf16 v[8:11], v[166:169], v[220:223], v[8:11]
	v_mfma_f32_16x16x32_bf16 v[52:55], v[170:173], v[192:195], v[52:55]
	v_mfma_f32_16x16x32_bf16 v[48:51], v[178:181], v[192:195], v[48:51]
	v_mfma_f32_16x16x32_bf16 v[36:39], v[170:173], v[200:203], v[36:39]
	v_mfma_f32_16x16x32_bf16 v[32:35], v[178:181], v[200:203], v[32:35]
	v_mfma_f32_16x16x32_bf16 v[20:23], v[170:173], v[208:211], v[20:23]
	v_mfma_f32_16x16x32_bf16 v[16:19], v[178:181], v[208:211], v[16:19]
	v_mfma_f32_16x16x32_bf16 v[4:7], v[170:173], v[216:219], v[4:7]
	v_mfma_f32_16x16x32_bf16 v[0:3], v[178:181], v[216:219], v[0:3]
	v_mfma_f32_16x16x32_bf16 v[52:55], v[174:177], v[196:199], v[52:55]
	v_mfma_f32_16x16x32_bf16 v[48:51], v[182:185], v[196:199], v[48:51]
	v_mfma_f32_16x16x32_bf16 v[36:39], v[174:177], v[204:207], v[36:39]
	v_mfma_f32_16x16x32_bf16 v[32:35], v[182:185], v[204:207], v[32:35]
	v_mfma_f32_16x16x32_bf16 v[20:23], v[174:177], v[212:215], v[20:23]
	v_mfma_f32_16x16x32_bf16 v[16:19], v[182:185], v[212:215], v[16:19]
	v_mfma_f32_16x16x32_bf16 v[4:7], v[174:177], v[220:223], v[4:7]
	v_mfma_f32_16x16x32_bf16 v[0:3], v[182:185], v[220:223], v[0:3]
	s_setprio 0
	s_barrier
	s_add_i32 s60, s60, 2
	s_add_u32 s58, s58, 0x100
	s_addc_u32 s59, s59, 0
	s_mov_b64 s[8:9], s[34:35]

; #define PG8_STAGE(bufoff, gbase, voff) do { _Pragma("unroll") for (int _i = 0; _i < 2; ++_i) \
;         __builtin_amdgcn_global_load_lds((const unsigned*)((const char*)(gbase) + (voff)[_i]), (PG8_LAS unsigned*)(lds + (bufoff) + ldsw + _i * 8192), 16, 0, 0); } while (0)
; #define PG8_LDA(dst, b, h) do { _Pragma("unroll") for (int m = 0; m < 4; ++m) _Pragma("unroll") for (int k = 0; k < 2; ++k) dst[m][k] = *(const PG8_LAS bf16x8*)(lds + PG8_SA(b, h) + aoff + m * 2048 + k * 1024); } while (0)
; #define PG8_LDB(dst, b, h) do { _Pragma("unroll") for (int n = 0; n < 2; ++n) _Pragma("unroll") for (int k = 0; k < 2; ++k) dst[n][k] = *(const PG8_LAS bf16x8*)(lds + PG8_SB(b, h) + boff + n * 2048 + k * 1024); } while (0)
; #define PG8_MMA(ai, bj, At, Bt) do { __builtin_amdgcn_s_setprio(1); _Pragma("unroll") for (int m = 0; m < 4; ++m) _Pragma("unroll") for (int n = 0; n < 2; ++n) _Pragma("unroll") for (int k = 0; k < 2; ++k) \
;         acc[ai][bj][m][n] = __builtin_amdgcn_mfma_f32_16x16x32_bf16(Bt[n][k], At[m][k], acc[ai][bj][m][n], 0, 0, 0); __builtin_amdgcn_s_setprio(0); } while (0)
; #define PG8_WAIT_V(n) asm volatile("s_waitcnt vmcnt(" #n ")" ::: "memory")
; #define PG8_WAIT_L(n) asm volatile("s_waitcnt lgkmcnt(" #n ")" ::: "memory")
; #define PG8_BAR __builtin_amdgcn_s_barrier()
; #define PG8_SCHED __builtin_amdgcn_sched_barrier(0)
; template <class Epi, class Sched, bool ALIGN_EPI = false, bool SP2 = false>
; __device__ __forceinline__ void gemm_phase(PG8_LAS unsigned char* lds, const Gemm g, const Sched& S, const Epi& E) {
;     ...
;             PG8_LDB(B0, 0, 0); PG8_LDB(B1, 0, 1); PG8_SCHED; PG8_LDA(At, 0, 0); PG8_STAGE(PG8_SA(1, 1), a1 + hstep, voffA);
;             PG8_WAIT_V(8); PG8_WAIT_L(0); PG8_BAR; PG8_MMA(0, 0, At, B0); PG8_MMA(0, 1, At, B1); PG8_BAR; PG8_SCHED;
;             PG8_LDA(At, 0, 1); PG8_STAGE(PG8_SB(0, 0), b2, voffB); PG8_STAGE(PG8_SB(0, 1), b2 + hstep, voffB); PG8_STAGE(PG8_SA(0, 0), a2, voffA);
;             PG8_WAIT_V(8); PG8_WAIT_L(0); PG8_BAR; PG8_MMA(1, 0, At, B0); PG8_MMA(1, 1, At, B1); PG8_BAR; PG8_SCHED;
.LBB0_373:
	s_ashr_i32 s31, s30, 31
	s_lshl_b64 s[34:35], s[30:31], 19
	v_readlane_b32 s36, v235, 31
	v_readlane_b32 s37, v235, 32
	s_add_u32 s34, s36, s34
	s_addc_u32 s35, s37, s35
	s_and_b64 s[36:37], s[6:7], exec
	s_cselect_b32 s1, s35, s3
	s_cselect_b32 s25, s34, s2
	s_ashr_i32 s29, s28, 31
	s_lshl_b64 s[36:37], s[28:29], 19
	s_add_u32 s36, s10, s36
	s_addc_u32 s37, s11, s37
	s_and_b64 s[40:41], s[6:7], exec
	s_cselect_b32 s29, s37, s39
	s_cselect_b32 s31, s36, s38
	s_add_u32 s2, s2, 0x40080
	s_addc_u32 s3, s3, 0
	s_add_u32 s58, s38, 0x100
	s_addc_u32 s59, s39, 0
	s_mov_b32 s60, -2
	ds_read_b128 v[128:131], v171
	ds_read_b128 v[132:135], v171 offset:1024
	ds_read_b128 v[136:139], v171 offset:2048
	ds_read_b128 v[140:143], v171 offset:3072
	ds_read_b128 v[164:167], v172
	ds_read_b128 v[178:181], v172 offset:1024
	ds_read_b128 v[182:185], v172 offset:2048
	ds_read_b128 v[192:195], v172 offset:3072
	s_add_u32 s38, s2, 0xfffc0080
	s_addc_u32 s39, s3, -1
	s_cmp_eq_u32 s60, 12
	s_cselect_b32 s41, s1, s39
	s_cselect_b32 s40, s25, s38
	s_cselect_b32 s39, s29, s59
	s_cselect_b32 s38, s31, s58
	v_lshl_add_u64 v[168:169], s[2:3], 0, v[156:157]
	s_add_i32 m0, s44, 0xc000
	ds_read_b128 v[196:199], v173
	ds_read_b128 v[200:203], v173 offset:1024
	ds_read_b128 v[204:207], v173 offset:2048
	ds_read_b128 v[208:211], v173 offset:3072
	ds_read_b128 v[212:215], v173 offset:4096
	ds_read_b128 v[216:219], v173 offset:5120
	ds_read_b128 v[220:223], v173 offset:6144
	ds_read_b128 v[224:227], v173 offset:7168
	global_load_lds_dwordx4 v[168:169], off
	v_lshl_add_u64 v[168:169], s[2:3], 0, v[158:159]
	s_add_i32 m0, s44, 0xe000
	s_nop 0
	global_load_lds_dwordx4 v[168:169], off
	s_waitcnt vmcnt(8)
	s_waitcnt lgkmcnt(0)
	s_barrier
	s_setprio 1
	v_mfma_f32_16x16x32_bf16 v[124:127], v[128:131], v[196:199], 0
	v_mfma_f32_16x16x32_bf16 v[120:123], v[136:139], v[196:199], 0
	v_mfma_f32_16x16x32_bf16 v[108:111], v[128:131], v[204:207], 0
	v_mfma_f32_16x16x32_bf16 v[104:107], v[136:139], v[204:207], 0
	v_mfma_f32_16x16x32_bf16 v[92:95], v[128:131], v[212:215], 0
	v_mfma_f32_16x16x32_bf16 v[88:91], v[136:139], v[212:215], 0
	v_mfma_f32_16x16x32_bf16 v[76:79], v[128:131], v[220:223], 0
	v_mfma_f32_16x16x32_bf16 v[72:75], v[136:139], v[220:223], 0
	v_mfma_f32_16x16x32_bf16 v[124:127], v[132:135], v[200:203], v[124:127]
	v_mfma_f32_16x16x32_bf16 v[120:123], v[140:143], v[200:203], v[120:123]
	v_mfma_f32_16x16x32_bf16 v[108:111], v[132:135], v[208:211], v[108:111]
	v_mfma_f32_16x16x32_bf16 v[104:107], v[140:143], v[208:211], v[104:107]
	v_mfma_f32_16x16x32_bf16 v[92:95], v[132:135], v[216:219], v[92:95]
	v_mfma_f32_16x16x32_bf16 v[88:91], v[140:143], v[216:219], v[88:91]
	v_mfma_f32_16x16x32_bf16 v[76:79], v[132:135], v[224:227], v[76:79]
	v_mfma_f32_16x16x32_bf16 v[72:75], v[140:143], v[224:227], v[72:75]
	v_mfma_f32_16x16x32_bf16 v[116:119], v[164:167], v[196:199], 0
	v_mfma_f32_16x16x32_bf16 v[112:115], v[182:185], v[196:199], 0
	v_mfma_f32_16x16x32_bf16 v[100:103], v[164:167], v[204:207], 0
	v_mfma_f32_16x16x32_bf16 v[96:99], v[182:185], v[204:207], 0
	v_mfma_f32_16x16x32_bf16 v[84:87], v[164:167], v[212:215], 0
	v_mfma_f32_16x16x32_bf16 v[80:83], v[182:185], v[212:215], 0
	v_mfma_f32_16x16x32_bf16 v[68:71], v[164:167], v[220:223], 0
	v_mfma_f32_16x16x32_bf16 v[64:67], v[182:185], v[220:223], 0
	v_mfma_f32_16x16x32_bf16 v[116:119], v[178:181], v[200:203], v[116:119]
	v_mfma_f32_16x16x32_bf16 v[112:115], v[192:195], v[200:203], v[112:115]
	v_mfma_f32_16x16x32_bf16 v[100:103], v[178:181], v[208:211], v[100:103]
	v_mfma_f32_16x16x32_bf16 v[96:99], v[192:195], v[208:211], v[96:99]
	v_mfma_f32_16x16x32_bf16 v[84:87], v[178:181], v[216:219], v[84:87]
	v_mfma_f32_16x16x32_bf16 v[80:83], v[192:195], v[216:219], v[80:83]
	v_mfma_f32_16x16x32_bf16 v[68:71], v[178:181], v[224:227], v[68:71]
	v_mfma_f32_16x16x32_bf16 v[64:67], v[192:195], v[224:227], v[64:67]
	s_setprio 0
	s_barrier
	s_add_i32 s61, s52, s33
	v_lshl_add_u64 v[168:169], s[38:39], 0, v[148:149]
	s_mov_b32 m0, s61
	ds_read_b128 v[196:199], v173 offset:16384
	ds_read_b128 v[200:203], v173 offset:17408
	ds_read_b128 v[204:207], v173 offset:18432
	ds_read_b128 v[208:211], v173 offset:19456
	ds_read_b128 v[212:215], v173 offset:20480
	ds_read_b128 v[216:219], v173 offset:21504
	ds_read_b128 v[220:223], v173 offset:22528
	ds_read_b128 v[224:227], v173 offset:23552
	global_load_lds_dwordx4 v[168:169], off
	s_add_i32 m0, s61, 0x2000
	s_add_u32 s62, s38, 0x40000
	v_lshl_add_u64 v[186:187], s[38:39], 0, v[144:145]
	s_addc_u32 s63, s39, 0
	s_add_i32 s61, s53, s33
	global_load_lds_dwordx4 v[186:187], off
	v_lshl_add_u64 v[228:229], s[62:63], 0, v[148:149]
	s_mov_b32 m0, s61
	v_lshl_add_u64 v[230:231], s[40:41], 0, v[146:147]
	global_load_lds_dwordx4 v[228:229], off
	v_lshl_add_u64 v[228:229], s[62:63], 0, v[144:145]
	s_add_i32 m0, s61, 0x2000
	s_nop 0
	global_load_lds_dwordx4 v[228:229], off
	v_lshl_add_u64 v[228:229], s[40:41], 0, v[150:151]
	s_mov_b32 m0, s44
	s_nop 0
	global_load_lds_dwordx4 v[228:229], off
	s_mov_b32 m0, s45
	s_nop 0
	global_load_lds_dwordx4 v[230:231], off
	s_waitcnt vmcnt(8)
	s_waitcnt lgkmcnt(0)
	s_barrier
; #define PG8_STAGE(bufoff, gbase, voff) do { _Pragma("unroll") for (int _i = 0; _i < 2; ++_i) \
;         __builtin_amdgcn_global_load_lds((const unsigned*)((const char*)(gbase) + (voff)[_i]), (PG8_LAS unsigned*)(lds + (bufoff) + ldsw + _i * 8192), 16, 0, 0); } while (0)
; #define PG8_LDA(dst, b, h) do { _Pragma("unroll") for (int m = 0; m < 4; ++m) _Pragma("unroll") for (int k = 0; k < 2; ++k) dst[m][k] = *(const PG8_LAS bf16x8*)(lds + PG8_SA(b, h) + aoff + m * 2048 + k * 1024); } while (0)
; #define PG8_LDB(dst, b, h) do { _Pragma("unroll") for (int n = 0; n < 2; ++n) _Pragma("unroll") for (int k = 0; k < 2; ++k) dst[n][k] = *(const PG8_LAS bf16x8*)(lds + PG8_SB(b, h) + boff + n * 2048 + k * 1024); } while (0)
; #define PG8_MMA(ai, bj, At, Bt) do { __builtin_amdgcn_s_setprio(1); _Pragma("unroll") for (int m = 0; m < 4; ++m) _Pragma("unroll") for (int n = 0; n < 2; ++n) _Pragma("unroll") for (int k = 0; k < 2; ++k) \
;         acc[ai][bj][m][n] = __builtin_amdgcn_mfma_f32_16x16x32_bf16(Bt[n][k], At[m][k], acc[ai][bj][m][n], 0, 0, 0); __builtin_amdgcn_s_setprio(0); } while (0)
; #define PG8_WAIT_V(n) asm volatile("s_waitcnt vmcnt(" #n ")" ::: "memory")
; #define PG8_WAIT_L(n) asm volatile("s_waitcnt lgkmcnt(" #n ")" ::: "memory")
; #define PG8_BAR __builtin_amdgcn_s_barrier()
; #define PG8_SCHED __builtin_amdgcn_sched_barrier(0)
; template <class Epi, class Sched, bool ALIGN_EPI = false, bool SP2 = false>
; __device__ __forceinline__ void gemm_phase(PG8_LAS unsigned char* lds, const Gemm g, const Sched& S, const Epi& E) {
;     ...
;             PG8_WAIT_V(8); PG8_WAIT_L(0); PG8_BAR; PG8_MMA(1, 0, At, B0); PG8_MMA(1, 1, At, B1); PG8_BAR; PG8_SCHED;
;             PG8_LDB(B0, 1, 0); PG8_LDB(B1, 1, 1); PG8_SCHED; PG8_LDA(At, 1, 0); PG8_STAGE(PG8_SA(0, 1), a2 + hstep, voffA);
;             PG8_WAIT_V(8); PG8_WAIT_L(0); PG8_BAR; PG8_MMA(0, 0, At, B0); PG8_MMA(0, 1, At, B1); PG8_BAR; PG8_SCHED;
	s_setprio 1
	v_mfma_f32_16x16x32_bf16 v[60:63], v[128:131], v[196:199], 0
	v_mfma_f32_16x16x32_bf16 v[56:59], v[136:139], v[196:199], 0
	v_mfma_f32_16x16x32_bf16 v[44:47], v[128:131], v[204:207], 0
	v_mfma_f32_16x16x32_bf16 v[40:43], v[136:139], v[204:207], 0
	v_mfma_f32_16x16x32_bf16 v[28:31], v[128:131], v[212:215], 0
	v_mfma_f32_16x16x32_bf16 v[24:27], v[136:139], v[212:215], 0
	v_mfma_f32_16x16x32_bf16 v[12:15], v[128:131], v[220:223], 0
	v_mfma_f32_16x16x32_bf16 v[8:11], v[136:139], v[220:223], 0
	v_mfma_f32_16x16x32_bf16 v[60:63], v[132:135], v[200:203], v[60:63]
	v_mfma_f32_16x16x32_bf16 v[56:59], v[140:143], v[200:203], v[56:59]
	v_mfma_f32_16x16x32_bf16 v[44:47], v[132:135], v[208:211], v[44:47]
	v_mfma_f32_16x16x32_bf16 v[40:43], v[140:143], v[208:211], v[40:43]
	v_mfma_f32_16x16x32_bf16 v[28:31], v[132:135], v[216:219], v[28:31]
	v_mfma_f32_16x16x32_bf16 v[24:27], v[140:143], v[216:219], v[24:27]
	v_mfma_f32_16x16x32_bf16 v[12:15], v[132:135], v[224:227], v[12:15]
	v_mfma_f32_16x16x32_bf16 v[8:11], v[140:143], v[224:227], v[8:11]
	v_mfma_f32_16x16x32_bf16 v[52:55], v[164:167], v[196:199], 0
	v_mfma_f32_16x16x32_bf16 v[48:51], v[182:185], v[196:199], 0
	v_mfma_f32_16x16x32_bf16 v[36:39], v[164:167], v[204:207], 0
	v_mfma_f32_16x16x32_bf16 v[32:35], v[182:185], v[204:207], 0
	v_mfma_f32_16x16x32_bf16 v[20:23], v[164:167], v[212:215], 0
	v_mfma_f32_16x16x32_bf16 v[16:19], v[182:185], v[212:215], 0
	v_mfma_f32_16x16x32_bf16 v[4:7], v[164:167], v[220:223], 0
	v_mfma_f32_16x16x32_bf16 v[0:3], v[182:185], v[220:223], 0
	v_mfma_f32_16x16x32_bf16 v[52:55], v[178:181], v[200:203], v[52:55]
	v_mfma_f32_16x16x32_bf16 v[48:51], v[192:195], v[200:203], v[48:51]
	v_mfma_f32_16x16x32_bf16 v[36:39], v[178:181], v[208:211], v[36:39]
	v_mfma_f32_16x16x32_bf16 v[32:35], v[192:195], v[208:211], v[32:35]
	v_mfma_f32_16x16x32_bf16 v[20:23], v[178:181], v[216:219], v[20:23]
	v_mfma_f32_16x16x32_bf16 v[16:19], v[192:195], v[216:219], v[16:19]
	v_mfma_f32_16x16x32_bf16 v[4:7], v[178:181], v[224:227], v[4:7]
	v_mfma_f32_16x16x32_bf16 v[0:3], v[192:195], v[224:227], v[0:3]
	s_setprio 0
	s_barrier
	s_add_i32 s61, 0, 0x18000
	s_add_i32 s62, 0, 0x1c000
	v_add_u32_e32 v140, s61, v170
	v_add_u32_e32 v152, s62, v170
	ds_read_b128 v[128:131], v140
	ds_read_b128 v[132:135], v140 offset:1024
	ds_read_b128 v[136:139], v140 offset:2048
	ds_read_b128 v[140:143], v140 offset:3072
	ds_read_b128 v[164:167], v152
	ds_read_b128 v[178:181], v152 offset:1024
	ds_read_b128 v[182:185], v152 offset:2048
	ds_read_b128 v[192:195], v152 offset:3072
	s_add_u32 s40, s40, 0x40000
	s_addc_u32 s41, s41, 0
	s_mov_b32 m0, s46
	v_lshl_add_u64 v[232:233], s[40:41], 0, v[150:151]
	ds_read_b128 v[196:199], v173 offset:32768
	ds_read_b128 v[200:203], v173 offset:33792
	ds_read_b128 v[204:207], v173 offset:34816
	ds_read_b128 v[208:211], v173 offset:35840
	ds_read_b128 v[212:215], v173 offset:36864
	ds_read_b128 v[216:219], v173 offset:37888
	ds_read_b128 v[220:223], v173 offset:38912
	ds_read_b128 v[224:227], v173 offset:39936
	global_load_lds_dwordx4 v[232:233], off
	v_lshl_add_u64 v[232:233], s[40:41], 0, v[146:147]
	s_mov_b32 m0, s47
	s_nop 0
	global_load_lds_dwordx4 v[232:233], off
	s_waitcnt vmcnt(8)
	s_waitcnt lgkmcnt(0)
	s_barrier
	s_setprio 1
	v_mfma_f32_16x16x32_bf16 v[124:127], v[128:131], v[196:199], v[124:127]
	v_mfma_f32_16x16x32_bf16 v[120:123], v[136:139], v[196:199], v[120:123]
	v_mfma_f32_16x16x32_bf16 v[108:111], v[128:131], v[204:207], v[108:111]
	v_mfma_f32_16x16x32_bf16 v[104:107], v[136:139], v[204:207], v[104:107]
	v_mfma_f32_16x16x32_bf16 v[92:95], v[128:131], v[212:215], v[92:95]
	v_mfma_f32_16x16x32_bf16 v[88:91], v[136:139], v[212:215], v[88:91]
	v_mfma_f32_16x16x32_bf16 v[76:79], v[128:131], v[220:223], v[76:79]
	v_mfma_f32_16x16x32_bf16 v[72:75], v[136:139], v[220:223], v[72:75]
	v_mfma_f32_16x16x32_bf16 v[124:127], v[132:135], v[200:203], v[124:127]
	v_mfma_f32_16x16x32_bf16 v[120:123], v[140:143], v[200:203], v[120:123]
	v_mfma_f32_16x16x32_bf16 v[108:111], v[132:135], v[208:211], v[108:111]
	v_mfma_f32_16x16x32_bf16 v[104:107], v[140:143], v[208:211], v[104:107]
	v_mfma_f32_16x16x32_bf16 v[92:95], v[132:135], v[216:219], v[92:95]
	v_mfma_f32_16x16x32_bf16 v[88:91], v[140:143], v[216:219], v[88:91]
	v_mfma_f32_16x16x32_bf16 v[76:79], v[132:135], v[224:227], v[76:79]
	v_mfma_f32_16x16x32_bf16 v[72:75], v[140:143], v[224:227], v[72:75]
	v_mfma_f32_16x16x32_bf16 v[116:119], v[164:167], v[196:199], v[116:119]
	v_mfma_f32_16x16x32_bf16 v[112:115], v[182:185], v[196:199], v[112:115]
	v_mfma_f32_16x16x32_bf16 v[100:103], v[164:167], v[204:207], v[100:103]
	v_mfma_f32_16x16x32_bf16 v[96:99], v[182:185], v[204:207], v[96:99]
	v_mfma_f32_16x16x32_bf16 v[84:87], v[164:167], v[212:215], v[84:87]
	v_mfma_f32_16x16x32_bf16 v[80:83], v[182:185], v[212:215], v[80:83]
	v_mfma_f32_16x16x32_bf16 v[68:71], v[164:167], v[220:223], v[68:71]
	v_mfma_f32_16x16x32_bf16 v[64:67], v[182:185], v[220:223], v[64:67]
	v_mfma_f32_16x16x32_bf16 v[116:119], v[178:181], v[200:203], v[116:119]
	v_mfma_f32_16x16x32_bf16 v[112:115], v[192:195], v[200:203], v[112:115]
	v_mfma_f32_16x16x32_bf16 v[100:103], v[178:181], v[208:211], v[100:103]
	v_mfma_f32_16x16x32_bf16 v[96:99], v[192:195], v[208:211], v[96:99]
	v_mfma_f32_16x16x32_bf16 v[84:87], v[178:181], v[216:219], v[84:87]
	v_mfma_f32_16x16x32_bf16 v[80:83], v[192:195], v[216:219], v[80:83]
	v_mfma_f32_16x16x32_bf16 v[68:71], v[178:181], v[224:227], v[68:71]
	v_mfma_f32_16x16x32_bf16 v[64:67], v[192:195], v[224:227], v[64:67]
	s_setprio 0
	s_barrier
; #define PG8_STAGE(bufoff, gbase, voff) do { _Pragma("unroll") for (int _i = 0; _i < 2; ++_i) \
;         __builtin_amdgcn_global_load_lds((const unsigned*)((const char*)(gbase) + (voff)[_i]), (PG8_LAS unsigned*)(lds + (bufoff) + ldsw + _i * 8192), 16, 0, 0); } while (0)
; #define PG8_LDA(dst, b, h) do { _Pragma("unroll") for (int m = 0; m < 4; ++m) _Pragma("unroll") for (int k = 0; k < 2; ++k) dst[m][k] = *(const PG8_LAS bf16x8*)(lds + PG8_SA(b, h) + aoff + m * 2048 + k * 1024); } while (0)
; #define PG8_MMA(ai, bj, At, Bt) do { __builtin_amdgcn_s_setprio(1); _Pragma("unroll") for (int m = 0; m < 4; ++m) _Pragma("unroll") for (int n = 0; n < 2; ++n) _Pragma("unroll") for (int k = 0; k < 2; ++k) \
;         acc[ai][bj][m][n] = __builtin_amdgcn_mfma_f32_16x16x32_bf16(Bt[n][k], At[m][k], acc[ai][bj][m][n], 0, 0, 0); __builtin_amdgcn_s_setprio(0); } while (0)
; #define PG8_WAIT_V(n) asm volatile("s_waitcnt vmcnt(" #n ")" ::: "memory")
; #define PG8_WAIT_L(n) asm volatile("s_waitcnt lgkmcnt(" #n ")" ::: "memory")
; #define PG8_BAR __builtin_amdgcn_s_barrier()
; #define PG8_SCHED __builtin_amdgcn_sched_barrier(0)
; template <class Epi, class Sched, bool ALIGN_EPI = false, bool SP2 = false>
; __device__ __forceinline__ void gemm_phase(PG8_LAS unsigned char* lds, const Gemm g, const Sched& S, const Epi& E) {
;     ...
;         for (int t = 0; t < nt; t += 2) {
;             const bool last = (t == nt - 2);
;             const char* a1 = cA + (size_t)(t + 1) * kstep;
;             const char* a2 = last ? nA : cA + (size_t)(t + 2) * kstep; const char* b2 = last ? nB : cB + (size_t)(t + 2) * kstep;
;     ...
;             PG8_LDA(At, 1, 1); PG8_STAGE(PG8_SB(1, 0), b3, voffB); PG8_STAGE(PG8_SB(1, 1), b3 + hstep, voffB); PG8_STAGE(PG8_SA(1, 0), a3, voffA);
;             PG8_WAIT_V(8); PG8_WAIT_L(0); PG8_BAR; PG8_MMA(1, 0, At, B0); PG8_MMA(1, 1, At, B1); PG8_BAR; PG8_SCHED;
	s_add_i32 s40, s61, s33
	v_lshl_add_u64 v[168:169], v[168:169], 0, s[16:17]
	s_mov_b32 m0, s40
	ds_read_b128 v[196:199], v173 offset:49152
	ds_read_b128 v[200:203], v173 offset:50176
	ds_read_b128 v[204:207], v173 offset:51200
	ds_read_b128 v[208:211], v173 offset:52224
	ds_read_b128 v[212:215], v173 offset:53248
	ds_read_b128 v[216:219], v173 offset:54272
	ds_read_b128 v[220:223], v173 offset:55296
	ds_read_b128 v[224:227], v173 offset:56320
	global_load_lds_dwordx4 v[168:169], off
	s_add_i32 m0, s40, 0x2000
	s_add_u32 s38, s38, 0x40080
	v_lshl_add_u64 v[168:169], v[186:187], 0, s[16:17]
	s_addc_u32 s39, s39, 0
	s_add_i32 s40, s62, s33
	global_load_lds_dwordx4 v[168:169], off
	v_lshl_add_u64 v[168:169], s[38:39], 0, v[148:149]
	s_mov_b32 m0, s40
	s_nop 0
	global_load_lds_dwordx4 v[168:169], off
	v_lshl_add_u64 v[168:169], s[38:39], 0, v[144:145]
	s_add_i32 m0, s40, 0x2000
	s_nop 0
	global_load_lds_dwordx4 v[168:169], off
	v_lshl_add_u64 v[168:169], v[228:229], 0, s[16:17]
	s_mov_b32 m0, s48
	s_nop 0
	global_load_lds_dwordx4 v[168:169], off
	v_lshl_add_u64 v[168:169], v[230:231], 0, s[16:17]
	s_mov_b32 m0, s49
	s_nop 0
	global_load_lds_dwordx4 v[168:169], off
	s_waitcnt vmcnt(8)
	s_waitcnt lgkmcnt(0)
	s_barrier
	s_setprio 1
	v_mfma_f32_16x16x32_bf16 v[60:63], v[128:131], v[196:199], v[60:63]
	v_mfma_f32_16x16x32_bf16 v[56:59], v[136:139], v[196:199], v[56:59]
	v_mfma_f32_16x16x32_bf16 v[44:47], v[128:131], v[204:207], v[44:47]
	v_mfma_f32_16x16x32_bf16 v[40:43], v[136:139], v[204:207], v[40:43]
	v_mfma_f32_16x16x32_bf16 v[28:31], v[128:131], v[212:215], v[28:31]
	v_mfma_f32_16x16x32_bf16 v[24:27], v[136:139], v[212:215], v[24:27]
	v_mfma_f32_16x16x32_bf16 v[12:15], v[128:131], v[220:223], v[12:15]
	v_mfma_f32_16x16x32_bf16 v[8:11], v[136:139], v[220:223], v[8:11]
	v_mfma_f32_16x16x32_bf16 v[60:63], v[132:135], v[200:203], v[60:63]
	v_mfma_f32_16x16x32_bf16 v[56:59], v[140:143], v[200:203], v[56:59]
	v_mfma_f32_16x16x32_bf16 v[44:47], v[132:135], v[208:211], v[44:47]
	v_mfma_f32_16x16x32_bf16 v[40:43], v[140:143], v[208:211], v[40:43]
	v_mfma_f32_16x16x32_bf16 v[28:31], v[132:135], v[216:219], v[28:31]
	v_mfma_f32_16x16x32_bf16 v[24:27], v[140:143], v[216:219], v[24:27]
	v_mfma_f32_16x16x32_bf16 v[12:15], v[132:135], v[224:227], v[12:15]
	v_mfma_f32_16x16x32_bf16 v[8:11], v[140:143], v[224:227], v[8:11]
	v_mfma_f32_16x16x32_bf16 v[52:55], v[164:167], v[196:199], v[52:55]
	v_mfma_f32_16x16x32_bf16 v[48:51], v[182:185], v[196:199], v[48:51]
	v_mfma_f32_16x16x32_bf16 v[36:39], v[164:167], v[204:207], v[36:39]
	v_mfma_f32_16x16x32_bf16 v[32:35], v[182:185], v[204:207], v[32:35]
	v_mfma_f32_16x16x32_bf16 v[20:23], v[164:167], v[212:215], v[20:23]
	v_mfma_f32_16x16x32_bf16 v[16:19], v[182:185], v[212:215], v[16:19]
	v_mfma_f32_16x16x32_bf16 v[4:7], v[164:167], v[220:223], v[4:7]
	v_mfma_f32_16x16x32_bf16 v[0:3], v[182:185], v[220:223], v[0:3]
	v_mfma_f32_16x16x32_bf16 v[52:55], v[178:181], v[200:203], v[52:55]
	v_mfma_f32_16x16x32_bf16 v[48:51], v[192:195], v[200:203], v[48:51]
	v_mfma_f32_16x16x32_bf16 v[36:39], v[178:181], v[208:211], v[36:39]
	v_mfma_f32_16x16x32_bf16 v[32:35], v[192:195], v[208:211], v[32:35]
	v_mfma_f32_16x16x32_bf16 v[20:23], v[178:181], v[216:219], v[20:23]
	v_mfma_f32_16x16x32_bf16 v[16:19], v[192:195], v[216:219], v[16:19]
	v_mfma_f32_16x16x32_bf16 v[4:7], v[178:181], v[224:227], v[4:7]
	v_mfma_f32_16x16x32_bf16 v[0:3], v[192:195], v[224:227], v[0:3]
	s_setprio 0
	s_barrier
	s_add_i32 s60, s60, 2
	s_add_u32 s2, s2, 0x100
	s_addc_u32 s3, s3, 0
	s_add_u32 s58, s58, 0x100
	s_addc_u32 s59, s59, 0

; #define PG8_STAGE(bufoff, gbase, voff) do { _Pragma("unroll") for (int _i = 0; _i < 2; ++_i) \
;         __builtin_amdgcn_global_load_lds((const unsigned*)((const char*)(gbase) + (voff)[_i]), (PG8_LAS unsigned*)(lds + (bufoff) + ldsw + _i * 8192), 16, 0, 0); } while (0)
; #define PG8_LDA(dst, b, h) do { _Pragma("unroll") for (int m = 0; m < 4; ++m) _Pragma("unroll") for (int k = 0; k < 2; ++k) dst[m][k] = *(const PG8_LAS bf16x8*)(lds + PG8_SA(b, h) + aoff + m * 2048 + k * 1024); } while (0)
; #define PG8_LDB(dst, b, h) do { _Pragma("unroll") for (int n = 0; n < 2; ++n) _Pragma("unroll") for (int k = 0; k < 2; ++k) dst[n][k] = *(const PG8_LAS bf16x8*)(lds + PG8_SB(b, h) + boff + n * 2048 + k * 1024); } while (0)
; #define PG8_WAIT_V(n) asm volatile("s_waitcnt vmcnt(" #n ")" ::: "memory")
; #define PG8_WAIT_L(n) asm volatile("s_waitcnt lgkmcnt(" #n ")" ::: "memory")
; #define PG8_BAR __builtin_amdgcn_s_barrier()
; #define PG8_SCHED __builtin_amdgcn_sched_barrier(0)
; template <class Epi, class Sched, bool ALIGN_EPI = false, bool SP2 = false>
; __device__ __forceinline__ void gemm_phase(PG8_LAS unsigned char* lds, const Gemm g, const Sched& S, const Epi& E) {
;     ...
;         const bool has_next = S.next(ui + 1, nxt);
;         const char* nA = has_next ? (const char*)g.A + (size_t)nxt.pm * tstep : cA; const char* nB = has_next ? (const char*)g.Bt + (size_t)nxt.pn * tstep : cB;
;         for (int t = 0; t < nt; t += 2) {
;             const bool last = (t == nt - 2);
;             const char* a1 = cA + (size_t)(t + 1) * kstep;
;             const char* a2 = last ? nA : cA + (size_t)(t + 2) * kstep; const char* b2 = last ? nB : cB + (size_t)(t + 2) * kstep;
;             const char* a3 = a2 + kstep; const char* b3 = b2 + kstep;
;             if (last && has_next) S.a_ready(nxt);
;             if constexpr (SP2) {
;             PG8_LDB(B0, 0, 0); PG8_LDB(B1, 0, 1); PG8_SCHED; PG8_LDA(At, 0, 0); PG8_STAGE(PG8_SA(1, 1), a1 + hstep, voffA);
;             PG8_WAIT_V(8); PG8_WAIT_L(0); PG8_BAR; PG8_MMA(0, 0, At, B0); PG8_MMA(0, 1, At, B1); PG8_BAR; PG8_SCHED;
;             PG8_LDA(At, 0, 1); PG8_STAGE(PG8_SB(0, 0), b2, voffB); PG8_STAGE(PG8_SB(0, 1), b2 + hstep, voffB); PG8_STAGE(PG8_SA(0, 0), a2, voffA);
;             PG8_WAIT_V(8); PG8_WAIT_L(0); PG8_BAR; PG8_MMA(1, 0, At, B0); PG8_MMA(1, 1, At, B1); PG8_BAR; PG8_SCHED;
.LBB0_697:
	s_ashr_i32 s17, s16, 31
	s_lshl_b64 s[18:19], s[16:17], 19
	v_readlane_b32 s48, v235, 2
	v_readlane_b32 s49, v235, 3
	s_add_u32 s18, s48, s18
	s_addc_u32 s19, s49, s19
	s_and_b64 s[20:21], s[6:7], exec
	s_cselect_b32 s17, s19, s27
	s_cselect_b32 s23, s18, s26
	s_ashr_i32 s15, s14, 31
	s_lshl_b64 s[20:21], s[14:15], 19
	s_add_u32 s20, s33, s20
	s_addc_u32 s21, s34, s21
	s_and_b64 s[30:31], s[6:7], exec
	s_cselect_b32 s15, s21, s29
	s_cselect_b32 s47, s20, s28
	s_add_u32 s26, s26, 0x40080
	s_addc_u32 s27, s27, 0
	v_readlane_b32 s50, v235, 4
	s_add_u32 s48, s28, 0x100
	s_addc_u32 s49, s29, 0
	s_mov_b32 s50, -2
	s_waitcnt lgkmcnt(0)
	v_readlane_b32 s51, v235, 5
	ds_read_b128 v[144:147], v151
	ds_read_b128 v[156:159], v151 offset:1024
	ds_read_b128 v[160:163], v151 offset:2048
	ds_read_b128 v[164:167], v151 offset:3072
	ds_read_b128 v[168:171], v152
	ds_read_b128 v[172:175], v152 offset:1024
	ds_read_b128 v[176:179], v152 offset:2048
	ds_read_b128 v[180:183], v152 offset:3072
	s_add_u32 s28, s26, 0xfffc0080
	s_addc_u32 s29, s27, -1
	s_cmp_eq_u32 s50, 12
	s_cselect_b32 s31, s17, s29
	s_cselect_b32 s30, s23, s28
	s_cselect_b32 s29, s15, s49
	s_cselect_b32 s28, s47, s48
	v_lshl_add_u64 v[218:219], s[26:27], 0, v[136:137]
	s_add_i32 m0, s25, 0xc000
	ds_read_b128 v[184:187], v153
	ds_read_b128 v[190:193], v153 offset:1024
	ds_read_b128 v[194:197], v153 offset:2048
	ds_read_b128 v[198:201], v153 offset:3072
	ds_read_b128 v[202:205], v153 offset:4096
	ds_read_b128 v[206:209], v153 offset:5120
	ds_read_b128 v[210:213], v153 offset:6144
	ds_read_b128 v[214:217], v153 offset:7168
	global_load_lds_dwordx4 v[218:219], off
	v_lshl_add_u64 v[218:219], s[26:27], 0, v[138:139]
	s_add_i32 m0, s25, 0xe000
	s_nop 0
	global_load_lds_dwordx4 v[218:219], off
	s_waitcnt vmcnt(8)
	s_waitcnt lgkmcnt(0)
	s_barrier
	s_setprio 1
	v_mfma_f32_16x16x32_bf16 v[124:127], v[144:147], v[184:187], 0
	v_mfma_f32_16x16x32_bf16 v[120:123], v[160:163], v[184:187], 0
	v_mfma_f32_16x16x32_bf16 v[108:111], v[144:147], v[194:197], 0
	v_mfma_f32_16x16x32_bf16 v[104:107], v[160:163], v[194:197], 0
	v_mfma_f32_16x16x32_bf16 v[92:95], v[144:147], v[202:205], 0
	v_mfma_f32_16x16x32_bf16 v[88:91], v[160:163], v[202:205], 0
	v_mfma_f32_16x16x32_bf16 v[76:79], v[144:147], v[210:213], 0
	v_mfma_f32_16x16x32_bf16 v[72:75], v[160:163], v[210:213], 0
	v_mfma_f32_16x16x32_bf16 v[124:127], v[156:159], v[190:193], v[124:127]
	v_mfma_f32_16x16x32_bf16 v[120:123], v[164:167], v[190:193], v[120:123]
	v_mfma_f32_16x16x32_bf16 v[108:111], v[156:159], v[198:201], v[108:111]
	v_mfma_f32_16x16x32_bf16 v[104:107], v[164:167], v[198:201], v[104:107]
	v_mfma_f32_16x16x32_bf16 v[92:95], v[156:159], v[206:209], v[92:95]
	v_mfma_f32_16x16x32_bf16 v[88:91], v[164:167], v[206:209], v[88:91]
	v_mfma_f32_16x16x32_bf16 v[76:79], v[156:159], v[214:217], v[76:79]
	v_mfma_f32_16x16x32_bf16 v[72:75], v[164:167], v[214:217], v[72:75]
	v_mfma_f32_16x16x32_bf16 v[116:119], v[168:171], v[184:187], 0
	v_mfma_f32_16x16x32_bf16 v[112:115], v[176:179], v[184:187], 0
	v_mfma_f32_16x16x32_bf16 v[100:103], v[168:171], v[194:197], 0
	v_mfma_f32_16x16x32_bf16 v[96:99], v[176:179], v[194:197], 0
	v_mfma_f32_16x16x32_bf16 v[84:87], v[168:171], v[202:205], 0
	v_mfma_f32_16x16x32_bf16 v[80:83], v[176:179], v[202:205], 0
	v_mfma_f32_16x16x32_bf16 v[68:71], v[168:171], v[210:213], 0
	v_mfma_f32_16x16x32_bf16 v[64:67], v[176:179], v[210:213], 0
	v_mfma_f32_16x16x32_bf16 v[116:119], v[172:175], v[190:193], v[116:119]
	v_mfma_f32_16x16x32_bf16 v[112:115], v[180:183], v[190:193], v[112:115]
	v_mfma_f32_16x16x32_bf16 v[100:103], v[172:175], v[198:201], v[100:103]
	v_mfma_f32_16x16x32_bf16 v[96:99], v[180:183], v[198:201], v[96:99]
	v_mfma_f32_16x16x32_bf16 v[84:87], v[172:175], v[206:209], v[84:87]
	v_mfma_f32_16x16x32_bf16 v[80:83], v[180:183], v[206:209], v[80:83]
	v_mfma_f32_16x16x32_bf16 v[68:71], v[172:175], v[214:217], v[68:71]
	v_mfma_f32_16x16x32_bf16 v[64:67], v[180:183], v[214:217], v[64:67]
	s_setprio 0
	s_barrier
	s_add_i32 s51, s45, s35
	v_lshl_add_u64 v[218:219], s[28:29], 0, v[130:131]
	s_mov_b32 m0, s51
	ds_read_b128 v[184:187], v153 offset:16384
	ds_read_b128 v[190:193], v153 offset:17408
	ds_read_b128 v[194:197], v153 offset:18432
	ds_read_b128 v[198:201], v153 offset:19456
	ds_read_b128 v[202:205], v153 offset:20480
	ds_read_b128 v[206:209], v153 offset:21504
	ds_read_b128 v[210:213], v153 offset:22528
	ds_read_b128 v[214:217], v153 offset:23552
	global_load_lds_dwordx4 v[218:219], off
	s_add_i32 m0, s51, 0x2000
	s_add_u32 s52, s28, 0x40000
	v_lshl_add_u64 v[220:221], s[28:29], 0, v[134:135]
	s_addc_u32 s53, s29, 0
	s_add_i32 s51, s46, s35
	global_load_lds_dwordx4 v[220:221], off
	v_lshl_add_u64 v[222:223], s[52:53], 0, v[130:131]
	s_mov_b32 m0, s51
	v_lshl_add_u64 v[224:225], s[30:31], 0, v[132:133]
	global_load_lds_dwordx4 v[222:223], off
	v_lshl_add_u64 v[222:223], s[52:53], 0, v[134:135]
	s_add_i32 m0, s51, 0x2000
	s_nop 0
	global_load_lds_dwordx4 v[222:223], off
	v_lshl_add_u64 v[222:223], s[30:31], 0, v[128:129]
	s_mov_b32 m0, s25
	s_nop 0
	global_load_lds_dwordx4 v[222:223], off
	s_mov_b32 m0, s36
	s_nop 0
	global_load_lds_dwordx4 v[224:225], off
	s_waitcnt vmcnt(8)
	s_waitcnt lgkmcnt(0)
	s_barrier
; #define PG8_STAGE(bufoff, gbase, voff) do { _Pragma("unroll") for (int _i = 0; _i < 2; ++_i) \
;         __builtin_amdgcn_global_load_lds((const unsigned*)((const char*)(gbase) + (voff)[_i]), (PG8_LAS unsigned*)(lds + (bufoff) + ldsw + _i * 8192), 16, 0, 0); } while (0)
; #define PG8_LDA(dst, b, h) do { _Pragma("unroll") for (int m = 0; m < 4; ++m) _Pragma("unroll") for (int k = 0; k < 2; ++k) dst[m][k] = *(const PG8_LAS bf16x8*)(lds + PG8_SA(b, h) + aoff + m * 2048 + k * 1024); } while (0)
; #define PG8_LDB(dst, b, h) do { _Pragma("unroll") for (int n = 0; n < 2; ++n) _Pragma("unroll") for (int k = 0; k < 2; ++k) dst[n][k] = *(const PG8_LAS bf16x8*)(lds + PG8_SB(b, h) + boff + n * 2048 + k * 1024); } while (0)
; #define PG8_MMA(ai, bj, At, Bt) do { __builtin_amdgcn_s_setprio(1); _Pragma("unroll") for (int m = 0; m < 4; ++m) _Pragma("unroll") for (int n = 0; n < 2; ++n) _Pragma("unroll") for (int k = 0; k < 2; ++k) \
;         acc[ai][bj][m][n] = __builtin_amdgcn_mfma_f32_16x16x32_bf16(Bt[n][k], At[m][k], acc[ai][bj][m][n], 0, 0, 0); __builtin_amdgcn_s_setprio(0); } while (0)
; #define PG8_WAIT_V(n) asm volatile("s_waitcnt vmcnt(" #n ")" ::: "memory")
; #define PG8_WAIT_L(n) asm volatile("s_waitcnt lgkmcnt(" #n ")" ::: "memory")
; #define PG8_BAR __builtin_amdgcn_s_barrier()
; #define PG8_SCHED __builtin_amdgcn_sched_barrier(0)
; template <class Epi, class Sched, bool ALIGN_EPI = false, bool SP2 = false>
; __device__ __forceinline__ void gemm_phase(PG8_LAS unsigned char* lds, const Gemm g, const Sched& S, const Epi& E) {
;     ...
;             PG8_LDA(At, 0, 1); PG8_STAGE(PG8_SB(0, 0), b2, voffB); PG8_STAGE(PG8_SB(0, 1), b2 + hstep, voffB); PG8_STAGE(PG8_SA(0, 0), a2, voffA);
;             PG8_WAIT_V(8); PG8_WAIT_L(0); PG8_BAR; PG8_MMA(1, 0, At, B0); PG8_MMA(1, 1, At, B1); PG8_BAR; PG8_SCHED;
;             PG8_LDB(B0, 1, 0); PG8_LDB(B1, 1, 1); PG8_SCHED; PG8_LDA(At, 1, 0); PG8_STAGE(PG8_SA(0, 1), a2 + hstep, voffA);
;             PG8_WAIT_V(8); PG8_WAIT_L(0); PG8_BAR; PG8_MMA(0, 0, At, B0); PG8_MMA(0, 1, At, B1); PG8_BAR; PG8_SCHED;
	s_setprio 1
	v_mfma_f32_16x16x32_bf16 v[60:63], v[144:147], v[184:187], 0
	v_mfma_f32_16x16x32_bf16 v[56:59], v[160:163], v[184:187], 0
	v_mfma_f32_16x16x32_bf16 v[44:47], v[144:147], v[194:197], 0
	v_mfma_f32_16x16x32_bf16 v[40:43], v[160:163], v[194:197], 0
	v_mfma_f32_16x16x32_bf16 v[28:31], v[144:147], v[202:205], 0
	v_mfma_f32_16x16x32_bf16 v[24:27], v[160:163], v[202:205], 0
	v_mfma_f32_16x16x32_bf16 v[12:15], v[144:147], v[210:213], 0
	v_mfma_f32_16x16x32_bf16 v[8:11], v[160:163], v[210:213], 0
	v_mfma_f32_16x16x32_bf16 v[60:63], v[156:159], v[190:193], v[60:63]
	v_mfma_f32_16x16x32_bf16 v[56:59], v[164:167], v[190:193], v[56:59]
	v_mfma_f32_16x16x32_bf16 v[44:47], v[156:159], v[198:201], v[44:47]
	v_mfma_f32_16x16x32_bf16 v[40:43], v[164:167], v[198:201], v[40:43]
	v_mfma_f32_16x16x32_bf16 v[28:31], v[156:159], v[206:209], v[28:31]
	v_mfma_f32_16x16x32_bf16 v[24:27], v[164:167], v[206:209], v[24:27]
	v_mfma_f32_16x16x32_bf16 v[12:15], v[156:159], v[214:217], v[12:15]
	v_mfma_f32_16x16x32_bf16 v[8:11], v[164:167], v[214:217], v[8:11]
	v_mfma_f32_16x16x32_bf16 v[52:55], v[168:171], v[184:187], 0
	v_mfma_f32_16x16x32_bf16 v[48:51], v[176:179], v[184:187], 0
	v_mfma_f32_16x16x32_bf16 v[36:39], v[168:171], v[194:197], 0
	v_mfma_f32_16x16x32_bf16 v[32:35], v[176:179], v[194:197], 0
	v_mfma_f32_16x16x32_bf16 v[20:23], v[168:171], v[202:205], 0
	v_mfma_f32_16x16x32_bf16 v[16:19], v[176:179], v[202:205], 0
	v_mfma_f32_16x16x32_bf16 v[4:7], v[168:171], v[210:213], 0
	v_mfma_f32_16x16x32_bf16 v[0:3], v[176:179], v[210:213], 0
	v_mfma_f32_16x16x32_bf16 v[52:55], v[172:175], v[190:193], v[52:55]
	v_mfma_f32_16x16x32_bf16 v[48:51], v[180:183], v[190:193], v[48:51]
	v_mfma_f32_16x16x32_bf16 v[36:39], v[172:175], v[198:201], v[36:39]
	v_mfma_f32_16x16x32_bf16 v[32:35], v[180:183], v[198:201], v[32:35]
	v_mfma_f32_16x16x32_bf16 v[20:23], v[172:175], v[206:209], v[20:23]
	v_mfma_f32_16x16x32_bf16 v[16:19], v[180:183], v[206:209], v[16:19]
	v_mfma_f32_16x16x32_bf16 v[4:7], v[172:175], v[214:217], v[4:7]
	v_mfma_f32_16x16x32_bf16 v[0:3], v[180:183], v[214:217], v[0:3]
	s_setprio 0
	s_barrier
	s_add_i32 s51, 0, 0x18000
	v_add_u32_e32 v155, s51, v149
	s_add_i32 s52, 0, 0x1c000
	ds_read_b128 v[144:147], v155
	ds_read_b128 v[156:159], v155 offset:1024
	ds_read_b128 v[160:163], v155 offset:2048
	ds_read_b128 v[164:167], v155 offset:3072
	v_add_u32_e32 v155, s52, v149
	ds_read_b128 v[168:171], v155
	ds_read_b128 v[172:175], v155 offset:1024
	ds_read_b128 v[176:179], v155 offset:2048
	ds_read_b128 v[180:183], v155 offset:3072
	s_add_u32 s30, s30, 0x40000
	s_addc_u32 s31, s31, 0
	s_mov_b32 m0, s37
	v_lshl_add_u64 v[226:227], s[30:31], 0, v[128:129]
	ds_read_b128 v[184:187], v153 offset:32768
	ds_read_b128 v[190:193], v153 offset:33792
	ds_read_b128 v[194:197], v153 offset:34816
	ds_read_b128 v[198:201], v153 offset:35840
	ds_read_b128 v[202:205], v153 offset:36864
	ds_read_b128 v[206:209], v153 offset:37888
	ds_read_b128 v[210:213], v153 offset:38912
	ds_read_b128 v[214:217], v153 offset:39936
	global_load_lds_dwordx4 v[226:227], off
	v_lshl_add_u64 v[226:227], s[30:31], 0, v[132:133]
	s_mov_b32 m0, s38
	s_nop 0
	global_load_lds_dwordx4 v[226:227], off
	s_waitcnt vmcnt(8)
	s_waitcnt lgkmcnt(0)
	s_barrier
	s_setprio 1
	v_mfma_f32_16x16x32_bf16 v[124:127], v[144:147], v[184:187], v[124:127]
	v_mfma_f32_16x16x32_bf16 v[120:123], v[160:163], v[184:187], v[120:123]
	v_mfma_f32_16x16x32_bf16 v[108:111], v[144:147], v[194:197], v[108:111]
	v_mfma_f32_16x16x32_bf16 v[104:107], v[160:163], v[194:197], v[104:107]
	v_mfma_f32_16x16x32_bf16 v[92:95], v[144:147], v[202:205], v[92:95]
	v_mfma_f32_16x16x32_bf16 v[88:91], v[160:163], v[202:205], v[88:91]
	v_mfma_f32_16x16x32_bf16 v[76:79], v[144:147], v[210:213], v[76:79]
	v_mfma_f32_16x16x32_bf16 v[72:75], v[160:163], v[210:213], v[72:75]
	v_mfma_f32_16x16x32_bf16 v[124:127], v[156:159], v[190:193], v[124:127]
	v_mfma_f32_16x16x32_bf16 v[120:123], v[164:167], v[190:193], v[120:123]
	v_mfma_f32_16x16x32_bf16 v[108:111], v[156:159], v[198:201], v[108:111]
	v_mfma_f32_16x16x32_bf16 v[104:107], v[164:167], v[198:201], v[104:107]
	v_mfma_f32_16x16x32_bf16 v[92:95], v[156:159], v[206:209], v[92:95]
	v_mfma_f32_16x16x32_bf16 v[88:91], v[164:167], v[206:209], v[88:91]
	v_mfma_f32_16x16x32_bf16 v[76:79], v[156:159], v[214:217], v[76:79]
	v_mfma_f32_16x16x32_bf16 v[72:75], v[164:167], v[214:217], v[72:75]
	v_mfma_f32_16x16x32_bf16 v[116:119], v[168:171], v[184:187], v[116:119]
	v_mfma_f32_16x16x32_bf16 v[112:115], v[176:179], v[184:187], v[112:115]
	v_mfma_f32_16x16x32_bf16 v[100:103], v[168:171], v[194:197], v[100:103]
	v_mfma_f32_16x16x32_bf16 v[96:99], v[176:179], v[194:197], v[96:99]
	v_mfma_f32_16x16x32_bf16 v[84:87], v[168:171], v[202:205], v[84:87]
	v_mfma_f32_16x16x32_bf16 v[80:83], v[176:179], v[202:205], v[80:83]
	v_mfma_f32_16x16x32_bf16 v[68:71], v[168:171], v[210:213], v[68:71]
	v_mfma_f32_16x16x32_bf16 v[64:67], v[176:179], v[210:213], v[64:67]
	v_mfma_f32_16x16x32_bf16 v[116:119], v[172:175], v[190:193], v[116:119]
	v_mfma_f32_16x16x32_bf16 v[112:115], v[180:183], v[190:193], v[112:115]
	v_mfma_f32_16x16x32_bf16 v[100:103], v[172:175], v[198:201], v[100:103]
	v_mfma_f32_16x16x32_bf16 v[96:99], v[180:183], v[198:201], v[96:99]
	v_mfma_f32_16x16x32_bf16 v[84:87], v[172:175], v[206:209], v[84:87]
	v_mfma_f32_16x16x32_bf16 v[80:83], v[180:183], v[206:209], v[80:83]
	v_mfma_f32_16x16x32_bf16 v[68:71], v[172:175], v[214:217], v[68:71]
	v_mfma_f32_16x16x32_bf16 v[64:67], v[180:183], v[214:217], v[64:67]
	s_setprio 0
	s_barrier
; #define PG8_STAGE(bufoff, gbase, voff) do { _Pragma("unroll") for (int _i = 0; _i < 2; ++_i) \
;         __builtin_amdgcn_global_load_lds((const unsigned*)((const char*)(gbase) + (voff)[_i]), (PG8_LAS unsigned*)(lds + (bufoff) + ldsw + _i * 8192), 16, 0, 0); } while (0)
; #define PG8_LDA(dst, b, h) do { _Pragma("unroll") for (int m = 0; m < 4; ++m) _Pragma("unroll") for (int k = 0; k < 2; ++k) dst[m][k] = *(const PG8_LAS bf16x8*)(lds + PG8_SA(b, h) + aoff + m * 2048 + k * 1024); } while (0)
; #define PG8_MMA(ai, bj, At, Bt) do { __builtin_amdgcn_s_setprio(1); _Pragma("unroll") for (int m = 0; m < 4; ++m) _Pragma("unroll") for (int n = 0; n < 2; ++n) _Pragma("unroll") for (int k = 0; k < 2; ++k) \
;         acc[ai][bj][m][n] = __builtin_amdgcn_mfma_f32_16x16x32_bf16(Bt[n][k], At[m][k], acc[ai][bj][m][n], 0, 0, 0); __builtin_amdgcn_s_setprio(0); } while (0)
; #define PG8_WAIT_V(n) asm volatile("s_waitcnt vmcnt(" #n ")" ::: "memory")
; #define PG8_WAIT_L(n) asm volatile("s_waitcnt lgkmcnt(" #n ")" ::: "memory")
; #define PG8_BAR __builtin_amdgcn_s_barrier()
; #define PG8_SCHED __builtin_amdgcn_sched_barrier(0)
; template <class Epi, class Sched, bool ALIGN_EPI = false, bool SP2 = false>
; __device__ __forceinline__ void gemm_phase(PG8_LAS unsigned char* lds, const Gemm g, const Sched& S, const Epi& E) {
;     ...
;             PG8_LDA(At, 1, 1); PG8_STAGE(PG8_SB(1, 0), b3, voffB); PG8_STAGE(PG8_SB(1, 1), b3 + hstep, voffB); PG8_STAGE(PG8_SA(1, 0), a3, voffA);
;             PG8_WAIT_V(8); PG8_WAIT_L(0); PG8_BAR; PG8_MMA(1, 0, At, B0); PG8_MMA(1, 1, At, B1); PG8_BAR; PG8_SCHED;
	s_add_i32 s30, s51, s35
	v_lshl_add_u64 v[218:219], v[218:219], 0, s[2:3]
	s_mov_b32 m0, s30
	ds_read_b128 v[184:187], v153 offset:49152
	ds_read_b128 v[190:193], v153 offset:50176
	ds_read_b128 v[194:197], v153 offset:51200
	ds_read_b128 v[198:201], v153 offset:52224
	ds_read_b128 v[202:205], v153 offset:53248
	ds_read_b128 v[206:209], v153 offset:54272
	ds_read_b128 v[210:213], v153 offset:55296
	ds_read_b128 v[214:217], v153 offset:56320
	global_load_lds_dwordx4 v[218:219], off
	s_add_i32 m0, s30, 0x2000
	s_add_u32 s28, s28, 0x40080
	v_lshl_add_u64 v[218:219], v[220:221], 0, s[2:3]
	s_addc_u32 s29, s29, 0
	s_add_i32 s30, s52, s35
	global_load_lds_dwordx4 v[218:219], off
	v_lshl_add_u64 v[218:219], s[28:29], 0, v[130:131]
	s_mov_b32 m0, s30
	s_nop 0
	global_load_lds_dwordx4 v[218:219], off
	v_lshl_add_u64 v[218:219], s[28:29], 0, v[134:135]
	s_add_i32 m0, s30, 0x2000
	s_nop 0
	global_load_lds_dwordx4 v[218:219], off
	v_lshl_add_u64 v[218:219], v[222:223], 0, s[2:3]
	s_mov_b32 m0, s40
	s_nop 0
	global_load_lds_dwordx4 v[218:219], off
	v_lshl_add_u64 v[218:219], v[224:225], 0, s[2:3]
	s_mov_b32 m0, s41
	s_nop 0
	global_load_lds_dwordx4 v[218:219], off
	s_waitcnt vmcnt(8)
	s_waitcnt lgkmcnt(0)
	s_barrier
	s_setprio 1
	v_mfma_f32_16x16x32_bf16 v[60:63], v[144:147], v[184:187], v[60:63]
	v_mfma_f32_16x16x32_bf16 v[56:59], v[160:163], v[184:187], v[56:59]
	v_mfma_f32_16x16x32_bf16 v[44:47], v[144:147], v[194:197], v[44:47]
	v_mfma_f32_16x16x32_bf16 v[40:43], v[160:163], v[194:197], v[40:43]
	v_mfma_f32_16x16x32_bf16 v[28:31], v[144:147], v[202:205], v[28:31]
	v_mfma_f32_16x16x32_bf16 v[24:27], v[160:163], v[202:205], v[24:27]
	v_mfma_f32_16x16x32_bf16 v[12:15], v[144:147], v[210:213], v[12:15]
	v_mfma_f32_16x16x32_bf16 v[8:11], v[160:163], v[210:213], v[8:11]
	v_mfma_f32_16x16x32_bf16 v[60:63], v[156:159], v[190:193], v[60:63]
	v_mfma_f32_16x16x32_bf16 v[56:59], v[164:167], v[190:193], v[56:59]
	v_mfma_f32_16x16x32_bf16 v[44:47], v[156:159], v[198:201], v[44:47]
	v_mfma_f32_16x16x32_bf16 v[40:43], v[164:167], v[198:201], v[40:43]
	v_mfma_f32_16x16x32_bf16 v[28:31], v[156:159], v[206:209], v[28:31]
	v_mfma_f32_16x16x32_bf16 v[24:27], v[164:167], v[206:209], v[24:27]
	v_mfma_f32_16x16x32_bf16 v[12:15], v[156:159], v[214:217], v[12:15]
	v_mfma_f32_16x16x32_bf16 v[8:11], v[164:167], v[214:217], v[8:11]
	v_mfma_f32_16x16x32_bf16 v[52:55], v[168:171], v[184:187], v[52:55]
	v_mfma_f32_16x16x32_bf16 v[48:51], v[176:179], v[184:187], v[48:51]
	v_mfma_f32_16x16x32_bf16 v[36:39], v[168:171], v[194:197], v[36:39]
	v_mfma_f32_16x16x32_bf16 v[32:35], v[176:179], v[194:197], v[32:35]
	v_mfma_f32_16x16x32_bf16 v[20:23], v[168:171], v[202:205], v[20:23]
	v_mfma_f32_16x16x32_bf16 v[16:19], v[176:179], v[202:205], v[16:19]
	v_mfma_f32_16x16x32_bf16 v[4:7], v[168:171], v[210:213], v[4:7]
	v_mfma_f32_16x16x32_bf16 v[0:3], v[176:179], v[210:213], v[0:3]
	v_mfma_f32_16x16x32_bf16 v[52:55], v[172:175], v[190:193], v[52:55]
	v_mfma_f32_16x16x32_bf16 v[48:51], v[180:183], v[190:193], v[48:51]
	v_mfma_f32_16x16x32_bf16 v[36:39], v[172:175], v[198:201], v[36:39]
	v_mfma_f32_16x16x32_bf16 v[32:35], v[180:183], v[198:201], v[32:35]
	v_mfma_f32_16x16x32_bf16 v[20:23], v[172:175], v[206:209], v[20:23]
	v_mfma_f32_16x16x32_bf16 v[16:19], v[180:183], v[206:209], v[16:19]
	v_mfma_f32_16x16x32_bf16 v[4:7], v[172:175], v[214:217], v[4:7]
	v_mfma_f32_16x16x32_bf16 v[0:3], v[180:183], v[214:217], v[0:3]
	s_setprio 0
	s_barrier
	s_add_i32 s50, s50, 2
	s_add_u32 s26, s26, 0x100
	s_addc_u32 s27, s27, 0
	s_add_u32 s48, s48, 0x100
	s_addc_u32 s49, s49, 0

; #define PG8_STAGE(bufoff, gbase, voff) do { _Pragma("unroll") for (int _i = 0; _i < 2; ++_i) \
;         __builtin_amdgcn_global_load_lds((const unsigned*)((const char*)(gbase) + (voff)[_i]), (PG8_LAS unsigned*)(lds + (bufoff) + ldsw + _i * 8192), 16, 0, 0); } while (0)
; #define PG8_LDA(dst, b, h) do { _Pragma("unroll") for (int m = 0; m < 4; ++m) _Pragma("unroll") for (int k = 0; k < 2; ++k) dst[m][k] = *(const PG8_LAS bf16x8*)(lds + PG8_SA(b, h) + aoff + m * 2048 + k * 1024); } while (0)
; #define PG8_LDB(dst, b, h) do { _Pragma("unroll") for (int n = 0; n < 2; ++n) _Pragma("unroll") for (int k = 0; k < 2; ++k) dst[n][k] = *(const PG8_LAS bf16x8*)(lds + PG8_SB(b, h) + boff + n * 2048 + k * 1024); } while (0)
; #define PG8_WAIT_V(n) asm volatile("s_waitcnt vmcnt(" #n ")" ::: "memory")
; #define PG8_WAIT_L(n) asm volatile("s_waitcnt lgkmcnt(" #n ")" ::: "memory")
; #define PG8_BAR __builtin_amdgcn_s_barrier()
; #define PG8_SCHED __builtin_amdgcn_sched_barrier(0)
; template <class Epi, class Sched, bool ALIGN_EPI = false, bool SP2 = false>
; __device__ __forceinline__ void gemm_phase(PG8_LAS unsigned char* lds, const Gemm g, const Sched& S, const Epi& E) {
;     ...
;         const bool has_next = S.next(ui + 1, nxt);
;         const char* nA = has_next ? (const char*)g.A + (size_t)nxt.pm * tstep : cA; const char* nB = has_next ? (const char*)g.Bt + (size_t)nxt.pn * tstep : cB;
;         for (int t = 0; t < nt; t += 2) {
;             const bool last = (t == nt - 2);
;             const char* a1 = cA + (size_t)(t + 1) * kstep;
;             const char* a2 = last ? nA : cA + (size_t)(t + 2) * kstep; const char* b2 = last ? nB : cB + (size_t)(t + 2) * kstep;
;             const char* a3 = a2 + kstep; const char* b3 = b2 + kstep;
;             if (last && has_next) S.a_ready(nxt);
;             if constexpr (SP2) {
;             PG8_LDB(B0, 0, 0); PG8_LDB(B1, 0, 1); PG8_SCHED; PG8_LDA(At, 0, 0); PG8_STAGE(PG8_SA(1, 1), a1 + hstep, voffA);
;             PG8_WAIT_V(8); PG8_WAIT_L(0); PG8_BAR; PG8_MMA(0, 0, At, B0); PG8_MMA(0, 1, At, B1); PG8_BAR; PG8_SCHED;
;             PG8_LDA(At, 0, 1); PG8_STAGE(PG8_SB(0, 0), b2, voffB); PG8_STAGE(PG8_SB(0, 1), b2 + hstep, voffB); PG8_STAGE(PG8_SA(0, 0), a2, voffA);
;             PG8_WAIT_V(8); PG8_WAIT_L(0); PG8_BAR; PG8_MMA(1, 0, At, B0); PG8_MMA(1, 1, At, B1); PG8_BAR; PG8_SCHED;
.LBB0_781:
	s_ashr_i32 s17, s16, 31
	s_lshl_b64 s[18:19], s[16:17], 19
	s_add_u32 s18, s8, s18
	s_addc_u32 s19, s9, s19
	s_and_b64 s[20:21], s[4:5], exec
	s_cselect_b32 s17, s19, s23
	s_cselect_b32 s47, s18, s22
	s_ashr_i32 s15, s14, 31
	s_lshl_b64 s[20:21], s[14:15], 19
	s_add_u32 s20, s28, s20
	s_addc_u32 s21, s29, s21
	s_and_b64 s[26:27], s[4:5], exec
	s_cselect_b32 s15, s21, s25
	s_cselect_b32 s48, s20, s24
	s_add_u32 s22, s22, 0x40080
	s_addc_u32 s23, s23, 0
	s_add_u32 s49, s24, 0x100
	s_addc_u32 s50, s25, 0
	s_mov_b32 s51, -2
	ds_read_b128 v[144:147], v151
	ds_read_b128 v[156:159], v151 offset:1024
	ds_read_b128 v[160:163], v151 offset:2048
	ds_read_b128 v[164:167], v151 offset:3072
	ds_read_b128 v[168:171], v152
	ds_read_b128 v[172:175], v152 offset:1024
	ds_read_b128 v[176:179], v152 offset:2048
	ds_read_b128 v[180:183], v152 offset:3072
	s_add_u32 s24, s22, 0xfffc0080
	s_addc_u32 s25, s23, -1
	s_cmp_eq_u32 s51, 12
	s_cselect_b32 s27, s17, s25
	s_cselect_b32 s26, s47, s24
	s_cselect_b32 s25, s15, s50
	s_cselect_b32 s24, s48, s49
	v_lshl_add_u64 v[218:219], s[22:23], 0, v[136:137]
	s_add_i32 m0, s34, 0xc000
	ds_read_b128 v[184:187], v153
	ds_read_b128 v[190:193], v153 offset:1024
	ds_read_b128 v[194:197], v153 offset:2048
	ds_read_b128 v[198:201], v153 offset:3072
	ds_read_b128 v[202:205], v153 offset:4096
	ds_read_b128 v[206:209], v153 offset:5120
	ds_read_b128 v[210:213], v153 offset:6144
	ds_read_b128 v[214:217], v153 offset:7168
	global_load_lds_dwordx4 v[218:219], off
	v_lshl_add_u64 v[218:219], s[22:23], 0, v[138:139]
	s_add_i32 m0, s34, 0xe000
	s_nop 0
	global_load_lds_dwordx4 v[218:219], off
	s_waitcnt vmcnt(8)
	s_waitcnt lgkmcnt(0)
	s_barrier
	s_setprio 1
	v_mfma_f32_16x16x32_bf16 v[116:119], v[144:147], v[184:187], 0
	v_mfma_f32_16x16x32_bf16 v[112:115], v[160:163], v[184:187], 0
	v_mfma_f32_16x16x32_bf16 v[100:103], v[144:147], v[194:197], 0
	v_mfma_f32_16x16x32_bf16 v[96:99], v[160:163], v[194:197], 0
	v_mfma_f32_16x16x32_bf16 v[84:87], v[144:147], v[202:205], 0
	v_mfma_f32_16x16x32_bf16 v[80:83], v[160:163], v[202:205], 0
	v_mfma_f32_16x16x32_bf16 v[72:75], v[144:147], v[210:213], 0
	v_mfma_f32_16x16x32_bf16 v[64:67], v[160:163], v[210:213], 0
	v_mfma_f32_16x16x32_bf16 v[116:119], v[156:159], v[190:193], v[116:119]
	v_mfma_f32_16x16x32_bf16 v[112:115], v[164:167], v[190:193], v[112:115]
	v_mfma_f32_16x16x32_bf16 v[100:103], v[156:159], v[198:201], v[100:103]
	v_mfma_f32_16x16x32_bf16 v[96:99], v[164:167], v[198:201], v[96:99]
	v_mfma_f32_16x16x32_bf16 v[84:87], v[156:159], v[206:209], v[84:87]
	v_mfma_f32_16x16x32_bf16 v[80:83], v[164:167], v[206:209], v[80:83]
	v_mfma_f32_16x16x32_bf16 v[72:75], v[156:159], v[214:217], v[72:75]
	v_mfma_f32_16x16x32_bf16 v[64:67], v[164:167], v[214:217], v[64:67]
	v_mfma_f32_16x16x32_bf16 v[124:127], v[168:171], v[184:187], 0
	v_mfma_f32_16x16x32_bf16 v[120:123], v[176:179], v[184:187], 0
	v_mfma_f32_16x16x32_bf16 v[108:111], v[168:171], v[194:197], 0
	v_mfma_f32_16x16x32_bf16 v[104:107], v[176:179], v[194:197], 0
	v_mfma_f32_16x16x32_bf16 v[92:95], v[168:171], v[202:205], 0
	v_mfma_f32_16x16x32_bf16 v[88:91], v[176:179], v[202:205], 0
	v_mfma_f32_16x16x32_bf16 v[76:79], v[168:171], v[210:213], 0
	v_mfma_f32_16x16x32_bf16 v[68:71], v[176:179], v[210:213], 0
	v_mfma_f32_16x16x32_bf16 v[124:127], v[172:175], v[190:193], v[124:127]
	v_mfma_f32_16x16x32_bf16 v[120:123], v[180:183], v[190:193], v[120:123]
	v_mfma_f32_16x16x32_bf16 v[108:111], v[172:175], v[198:201], v[108:111]
	v_mfma_f32_16x16x32_bf16 v[104:107], v[180:183], v[198:201], v[104:107]
	v_mfma_f32_16x16x32_bf16 v[92:95], v[172:175], v[206:209], v[92:95]
	v_mfma_f32_16x16x32_bf16 v[88:91], v[180:183], v[206:209], v[88:91]
	v_mfma_f32_16x16x32_bf16 v[76:79], v[172:175], v[214:217], v[76:79]
	v_mfma_f32_16x16x32_bf16 v[68:71], v[180:183], v[214:217], v[68:71]
	s_setprio 0
	s_barrier
	s_add_i32 s52, s43, s30
	v_lshl_add_u64 v[218:219], s[24:25], 0, v[132:133]
	s_mov_b32 m0, s52
	ds_read_b128 v[184:187], v153 offset:16384
	ds_read_b128 v[190:193], v153 offset:17408
	ds_read_b128 v[194:197], v153 offset:18432
	ds_read_b128 v[198:201], v153 offset:19456
	ds_read_b128 v[202:205], v153 offset:20480
	ds_read_b128 v[206:209], v153 offset:21504
	ds_read_b128 v[210:213], v153 offset:22528
	ds_read_b128 v[214:217], v153 offset:23552
	global_load_lds_dwordx4 v[218:219], off
	s_add_i32 m0, s52, 0x2000
	s_add_u32 s52, s24, 0x40000
	v_lshl_add_u64 v[220:221], s[24:25], 0, v[128:129]
	s_addc_u32 s53, s25, 0
	s_add_i32 s54, s44, s30
	global_load_lds_dwordx4 v[220:221], off
	v_lshl_add_u64 v[222:223], s[52:53], 0, v[132:133]
	s_mov_b32 m0, s54
	v_lshl_add_u64 v[224:225], s[26:27], 0, v[130:131]
	global_load_lds_dwordx4 v[222:223], off
	v_lshl_add_u64 v[222:223], s[52:53], 0, v[128:129]
	s_add_i32 m0, s54, 0x2000
	s_nop 0
	global_load_lds_dwordx4 v[222:223], off
	v_lshl_add_u64 v[222:223], s[26:27], 0, v[134:135]
	s_mov_b32 m0, s34
	s_nop 0
	global_load_lds_dwordx4 v[222:223], off
	s_mov_b32 m0, s35
	s_nop 0
	global_load_lds_dwordx4 v[224:225], off
	s_waitcnt vmcnt(8)
	s_waitcnt lgkmcnt(0)
	s_barrier
; #define PG8_STAGE(bufoff, gbase, voff) do { _Pragma("unroll") for (int _i = 0; _i < 2; ++_i) \
;         __builtin_amdgcn_global_load_lds((const unsigned*)((const char*)(gbase) + (voff)[_i]), (PG8_LAS unsigned*)(lds + (bufoff) + ldsw + _i * 8192), 16, 0, 0); } while (0)
; #define PG8_LDA(dst, b, h) do { _Pragma("unroll") for (int m = 0; m < 4; ++m) _Pragma("unroll") for (int k = 0; k < 2; ++k) dst[m][k] = *(const PG8_LAS bf16x8*)(lds + PG8_SA(b, h) + aoff + m * 2048 + k * 1024); } while (0)
; #define PG8_LDB(dst, b, h) do { _Pragma("unroll") for (int n = 0; n < 2; ++n) _Pragma("unroll") for (int k = 0; k < 2; ++k) dst[n][k] = *(const PG8_LAS bf16x8*)(lds + PG8_SB(b, h) + boff + n * 2048 + k * 1024); } while (0)
; #define PG8_MMA(ai, bj, At, Bt) do { __builtin_amdgcn_s_setprio(1); _Pragma("unroll") for (int m = 0; m < 4; ++m) _Pragma("unroll") for (int n = 0; n < 2; ++n) _Pragma("unroll") for (int k = 0; k < 2; ++k) \
;         acc[ai][bj][m][n] = __builtin_amdgcn_mfma_f32_16x16x32_bf16(Bt[n][k], At[m][k], acc[ai][bj][m][n], 0, 0, 0); __builtin_amdgcn_s_setprio(0); } while (0)
; #define PG8_WAIT_V(n) asm volatile("s_waitcnt vmcnt(" #n ")" ::: "memory")
; #define PG8_WAIT_L(n) asm volatile("s_waitcnt lgkmcnt(" #n ")" ::: "memory")
; #define PG8_BAR __builtin_amdgcn_s_barrier()
; #define PG8_SCHED __builtin_amdgcn_sched_barrier(0)
; template <class Epi, class Sched, bool ALIGN_EPI = false, bool SP2 = false>
; __device__ __forceinline__ void gemm_phase(PG8_LAS unsigned char* lds, const Gemm g, const Sched& S, const Epi& E) {
;     ...
;             PG8_LDA(At, 0, 1); PG8_STAGE(PG8_SB(0, 0), b2, voffB); PG8_STAGE(PG8_SB(0, 1), b2 + hstep, voffB); PG8_STAGE(PG8_SA(0, 0), a2, voffA);
;             PG8_WAIT_V(8); PG8_WAIT_L(0); PG8_BAR; PG8_MMA(1, 0, At, B0); PG8_MMA(1, 1, At, B1); PG8_BAR; PG8_SCHED;
;             PG8_LDB(B0, 1, 0); PG8_LDB(B1, 1, 1); PG8_SCHED; PG8_LDA(At, 1, 0); PG8_STAGE(PG8_SA(0, 1), a2 + hstep, voffA);
;             PG8_WAIT_V(8); PG8_WAIT_L(0); PG8_BAR; PG8_MMA(0, 0, At, B0); PG8_MMA(0, 1, At, B1); PG8_BAR; PG8_SCHED;
	s_setprio 1
	v_mfma_f32_16x16x32_bf16 v[56:59], v[144:147], v[184:187], 0
	v_mfma_f32_16x16x32_bf16 v[48:51], v[160:163], v[184:187], 0
	v_mfma_f32_16x16x32_bf16 v[40:43], v[144:147], v[194:197], 0
	v_mfma_f32_16x16x32_bf16 v[32:35], v[160:163], v[194:197], 0
	v_mfma_f32_16x16x32_bf16 v[24:27], v[144:147], v[202:205], 0
	v_mfma_f32_16x16x32_bf16 v[16:19], v[160:163], v[202:205], 0
	v_mfma_f32_16x16x32_bf16 v[8:11], v[144:147], v[210:213], 0
	v_mfma_f32_16x16x32_bf16 v[0:3], v[160:163], v[210:213], 0
	v_mfma_f32_16x16x32_bf16 v[56:59], v[156:159], v[190:193], v[56:59]
	v_mfma_f32_16x16x32_bf16 v[48:51], v[164:167], v[190:193], v[48:51]
	v_mfma_f32_16x16x32_bf16 v[40:43], v[156:159], v[198:201], v[40:43]
	v_mfma_f32_16x16x32_bf16 v[32:35], v[164:167], v[198:201], v[32:35]
	v_mfma_f32_16x16x32_bf16 v[24:27], v[156:159], v[206:209], v[24:27]
	v_mfma_f32_16x16x32_bf16 v[16:19], v[164:167], v[206:209], v[16:19]
	v_mfma_f32_16x16x32_bf16 v[8:11], v[156:159], v[214:217], v[8:11]
	v_mfma_f32_16x16x32_bf16 v[0:3], v[164:167], v[214:217], v[0:3]
	v_mfma_f32_16x16x32_bf16 v[60:63], v[168:171], v[184:187], 0
	v_mfma_f32_16x16x32_bf16 v[52:55], v[176:179], v[184:187], 0
	v_mfma_f32_16x16x32_bf16 v[44:47], v[168:171], v[194:197], 0
	v_mfma_f32_16x16x32_bf16 v[36:39], v[176:179], v[194:197], 0
	v_mfma_f32_16x16x32_bf16 v[28:31], v[168:171], v[202:205], 0
	v_mfma_f32_16x16x32_bf16 v[20:23], v[176:179], v[202:205], 0
	v_mfma_f32_16x16x32_bf16 v[12:15], v[168:171], v[210:213], 0
	v_mfma_f32_16x16x32_bf16 v[4:7], v[176:179], v[210:213], 0
	v_mfma_f32_16x16x32_bf16 v[60:63], v[172:175], v[190:193], v[60:63]
	v_mfma_f32_16x16x32_bf16 v[52:55], v[180:183], v[190:193], v[52:55]
	v_mfma_f32_16x16x32_bf16 v[44:47], v[172:175], v[198:201], v[44:47]
	v_mfma_f32_16x16x32_bf16 v[36:39], v[180:183], v[198:201], v[36:39]
	v_mfma_f32_16x16x32_bf16 v[28:31], v[172:175], v[206:209], v[28:31]
	v_mfma_f32_16x16x32_bf16 v[20:23], v[180:183], v[206:209], v[20:23]
	v_mfma_f32_16x16x32_bf16 v[12:15], v[172:175], v[214:217], v[12:15]
	v_mfma_f32_16x16x32_bf16 v[4:7], v[180:183], v[214:217], v[4:7]
	s_setprio 0
	s_barrier
	s_add_i32 s52, 0, 0x18000
	v_add_u32_e32 v155, s52, v149
	s_add_i32 s53, 0, 0x1c000
	ds_read_b128 v[144:147], v155
	ds_read_b128 v[156:159], v155 offset:1024
	ds_read_b128 v[160:163], v155 offset:2048
	ds_read_b128 v[164:167], v155 offset:3072
	v_add_u32_e32 v155, s53, v149
	ds_read_b128 v[168:171], v155
	ds_read_b128 v[172:175], v155 offset:1024
	ds_read_b128 v[176:179], v155 offset:2048
	ds_read_b128 v[180:183], v155 offset:3072
	s_add_u32 s26, s26, 0x40000
	s_addc_u32 s27, s27, 0
	s_mov_b32 m0, s36
	v_lshl_add_u64 v[226:227], s[26:27], 0, v[134:135]
	ds_read_b128 v[184:187], v153 offset:32768
	ds_read_b128 v[190:193], v153 offset:33792
	ds_read_b128 v[194:197], v153 offset:34816
	ds_read_b128 v[198:201], v153 offset:35840
	ds_read_b128 v[202:205], v153 offset:36864
	ds_read_b128 v[206:209], v153 offset:37888
	ds_read_b128 v[210:213], v153 offset:38912
	ds_read_b128 v[214:217], v153 offset:39936
	global_load_lds_dwordx4 v[226:227], off
	v_lshl_add_u64 v[226:227], s[26:27], 0, v[130:131]
	s_mov_b32 m0, s37
	s_nop 0
	global_load_lds_dwordx4 v[226:227], off
	s_waitcnt vmcnt(8)
	s_waitcnt lgkmcnt(0)
	s_barrier
	s_setprio 1
	v_mfma_f32_16x16x32_bf16 v[116:119], v[144:147], v[184:187], v[116:119]
	v_mfma_f32_16x16x32_bf16 v[112:115], v[160:163], v[184:187], v[112:115]
	v_mfma_f32_16x16x32_bf16 v[100:103], v[144:147], v[194:197], v[100:103]
	v_mfma_f32_16x16x32_bf16 v[96:99], v[160:163], v[194:197], v[96:99]
	v_mfma_f32_16x16x32_bf16 v[84:87], v[144:147], v[202:205], v[84:87]
	v_mfma_f32_16x16x32_bf16 v[80:83], v[160:163], v[202:205], v[80:83]
	v_mfma_f32_16x16x32_bf16 v[72:75], v[144:147], v[210:213], v[72:75]
	v_mfma_f32_16x16x32_bf16 v[64:67], v[160:163], v[210:213], v[64:67]
	v_mfma_f32_16x16x32_bf16 v[116:119], v[156:159], v[190:193], v[116:119]
	v_mfma_f32_16x16x32_bf16 v[112:115], v[164:167], v[190:193], v[112:115]
	v_mfma_f32_16x16x32_bf16 v[100:103], v[156:159], v[198:201], v[100:103]
	v_mfma_f32_16x16x32_bf16 v[96:99], v[164:167], v[198:201], v[96:99]
	v_mfma_f32_16x16x32_bf16 v[84:87], v[156:159], v[206:209], v[84:87]
	v_mfma_f32_16x16x32_bf16 v[80:83], v[164:167], v[206:209], v[80:83]
	v_mfma_f32_16x16x32_bf16 v[72:75], v[156:159], v[214:217], v[72:75]
	v_mfma_f32_16x16x32_bf16 v[64:67], v[164:167], v[214:217], v[64:67]
	v_mfma_f32_16x16x32_bf16 v[124:127], v[168:171], v[184:187], v[124:127]
	v_mfma_f32_16x16x32_bf16 v[120:123], v[176:179], v[184:187], v[120:123]
	v_mfma_f32_16x16x32_bf16 v[108:111], v[168:171], v[194:197], v[108:111]
	v_mfma_f32_16x16x32_bf16 v[104:107], v[176:179], v[194:197], v[104:107]
	v_mfma_f32_16x16x32_bf16 v[92:95], v[168:171], v[202:205], v[92:95]
	v_mfma_f32_16x16x32_bf16 v[88:91], v[176:179], v[202:205], v[88:91]
	v_mfma_f32_16x16x32_bf16 v[76:79], v[168:171], v[210:213], v[76:79]
	v_mfma_f32_16x16x32_bf16 v[68:71], v[176:179], v[210:213], v[68:71]
	v_mfma_f32_16x16x32_bf16 v[124:127], v[172:175], v[190:193], v[124:127]
	v_mfma_f32_16x16x32_bf16 v[120:123], v[180:183], v[190:193], v[120:123]
	v_mfma_f32_16x16x32_bf16 v[108:111], v[172:175], v[198:201], v[108:111]
	v_mfma_f32_16x16x32_bf16 v[104:107], v[180:183], v[198:201], v[104:107]
	v_mfma_f32_16x16x32_bf16 v[92:95], v[172:175], v[206:209], v[92:95]
	v_mfma_f32_16x16x32_bf16 v[88:91], v[180:183], v[206:209], v[88:91]
	v_mfma_f32_16x16x32_bf16 v[76:79], v[172:175], v[214:217], v[76:79]
	v_mfma_f32_16x16x32_bf16 v[68:71], v[180:183], v[214:217], v[68:71]
	s_setprio 0
	s_barrier
; #define PG8_STAGE(bufoff, gbase, voff) do { _Pragma("unroll") for (int _i = 0; _i < 2; ++_i) \
;         __builtin_amdgcn_global_load_lds((const unsigned*)((const char*)(gbase) + (voff)[_i]), (PG8_LAS unsigned*)(lds + (bufoff) + ldsw + _i * 8192), 16, 0, 0); } while (0)
; #define PG8_LDA(dst, b, h) do { _Pragma("unroll") for (int m = 0; m < 4; ++m) _Pragma("unroll") for (int k = 0; k < 2; ++k) dst[m][k] = *(const PG8_LAS bf16x8*)(lds + PG8_SA(b, h) + aoff + m * 2048 + k * 1024); } while (0)
; #define PG8_MMA(ai, bj, At, Bt) do { __builtin_amdgcn_s_setprio(1); _Pragma("unroll") for (int m = 0; m < 4; ++m) _Pragma("unroll") for (int n = 0; n < 2; ++n) _Pragma("unroll") for (int k = 0; k < 2; ++k) \
;         acc[ai][bj][m][n] = __builtin_amdgcn_mfma_f32_16x16x32_bf16(Bt[n][k], At[m][k], acc[ai][bj][m][n], 0, 0, 0); __builtin_amdgcn_s_setprio(0); } while (0)
; #define PG8_WAIT_V(n) asm volatile("s_waitcnt vmcnt(" #n ")" ::: "memory")
; #define PG8_WAIT_L(n) asm volatile("s_waitcnt lgkmcnt(" #n ")" ::: "memory")
; #define PG8_BAR __builtin_amdgcn_s_barrier()
; #define PG8_SCHED __builtin_amdgcn_sched_barrier(0)
; template <class Epi, class Sched, bool ALIGN_EPI = false, bool SP2 = false>
; __device__ __forceinline__ void gemm_phase(PG8_LAS unsigned char* lds, const Gemm g, const Sched& S, const Epi& E) {
;     ...
;             PG8_LDA(At, 1, 1); PG8_STAGE(PG8_SB(1, 0), b3, voffB); PG8_STAGE(PG8_SB(1, 1), b3 + hstep, voffB); PG8_STAGE(PG8_SA(1, 0), a3, voffA);
;             PG8_WAIT_V(8); PG8_WAIT_L(0); PG8_BAR; PG8_MMA(1, 0, At, B0); PG8_MMA(1, 1, At, B1); PG8_BAR; PG8_SCHED;
	s_add_i32 s26, s52, s30
	v_lshl_add_u64 v[218:219], v[218:219], 0, s[6:7]
	s_mov_b32 m0, s26
	ds_read_b128 v[184:187], v153 offset:49152
	ds_read_b128 v[190:193], v153 offset:50176
	ds_read_b128 v[194:197], v153 offset:51200
	ds_read_b128 v[198:201], v153 offset:52224
	ds_read_b128 v[202:205], v153 offset:53248
	ds_read_b128 v[206:209], v153 offset:54272
	ds_read_b128 v[210:213], v153 offset:55296
	ds_read_b128 v[214:217], v153 offset:56320
	global_load_lds_dwordx4 v[218:219], off
	s_add_i32 m0, s26, 0x2000
	s_add_u32 s24, s24, 0x40080
	v_lshl_add_u64 v[218:219], v[220:221], 0, s[6:7]
	s_addc_u32 s25, s25, 0
	s_add_i32 s26, s53, s30
	global_load_lds_dwordx4 v[218:219], off
	v_lshl_add_u64 v[218:219], s[24:25], 0, v[132:133]
	s_mov_b32 m0, s26
	s_nop 0
	global_load_lds_dwordx4 v[218:219], off
	v_lshl_add_u64 v[218:219], s[24:25], 0, v[128:129]
	s_add_i32 m0, s26, 0x2000
	s_nop 0
	global_load_lds_dwordx4 v[218:219], off
	v_lshl_add_u64 v[218:219], v[222:223], 0, s[6:7]
	s_mov_b32 m0, s39
	s_nop 0
	global_load_lds_dwordx4 v[218:219], off
	v_lshl_add_u64 v[218:219], v[224:225], 0, s[6:7]
	s_mov_b32 m0, s40
	s_nop 0
	global_load_lds_dwordx4 v[218:219], off
	s_waitcnt vmcnt(8)
	s_waitcnt lgkmcnt(0)
	s_barrier
	s_setprio 1
	v_mfma_f32_16x16x32_bf16 v[56:59], v[144:147], v[184:187], v[56:59]
	v_mfma_f32_16x16x32_bf16 v[48:51], v[160:163], v[184:187], v[48:51]
	v_mfma_f32_16x16x32_bf16 v[40:43], v[144:147], v[194:197], v[40:43]
	v_mfma_f32_16x16x32_bf16 v[32:35], v[160:163], v[194:197], v[32:35]
	v_mfma_f32_16x16x32_bf16 v[24:27], v[144:147], v[202:205], v[24:27]
	v_mfma_f32_16x16x32_bf16 v[16:19], v[160:163], v[202:205], v[16:19]
	v_mfma_f32_16x16x32_bf16 v[8:11], v[144:147], v[210:213], v[8:11]
	v_mfma_f32_16x16x32_bf16 v[0:3], v[160:163], v[210:213], v[0:3]
	v_mfma_f32_16x16x32_bf16 v[56:59], v[156:159], v[190:193], v[56:59]
	v_mfma_f32_16x16x32_bf16 v[48:51], v[164:167], v[190:193], v[48:51]
	v_mfma_f32_16x16x32_bf16 v[40:43], v[156:159], v[198:201], v[40:43]
	v_mfma_f32_16x16x32_bf16 v[32:35], v[164:167], v[198:201], v[32:35]
	v_mfma_f32_16x16x32_bf16 v[24:27], v[156:159], v[206:209], v[24:27]
	v_mfma_f32_16x16x32_bf16 v[16:19], v[164:167], v[206:209], v[16:19]
	v_mfma_f32_16x16x32_bf16 v[8:11], v[156:159], v[214:217], v[8:11]
	v_mfma_f32_16x16x32_bf16 v[0:3], v[164:167], v[214:217], v[0:3]
	v_mfma_f32_16x16x32_bf16 v[60:63], v[168:171], v[184:187], v[60:63]
	v_mfma_f32_16x16x32_bf16 v[52:55], v[176:179], v[184:187], v[52:55]
	v_mfma_f32_16x16x32_bf16 v[44:47], v[168:171], v[194:197], v[44:47]
	v_mfma_f32_16x16x32_bf16 v[36:39], v[176:179], v[194:197], v[36:39]
	v_mfma_f32_16x16x32_bf16 v[28:31], v[168:171], v[202:205], v[28:31]
	v_mfma_f32_16x16x32_bf16 v[20:23], v[176:179], v[202:205], v[20:23]
	v_mfma_f32_16x16x32_bf16 v[12:15], v[168:171], v[210:213], v[12:15]
	v_mfma_f32_16x16x32_bf16 v[4:7], v[176:179], v[210:213], v[4:7]
	v_mfma_f32_16x16x32_bf16 v[60:63], v[172:175], v[190:193], v[60:63]
	v_mfma_f32_16x16x32_bf16 v[52:55], v[180:183], v[190:193], v[52:55]
	v_mfma_f32_16x16x32_bf16 v[44:47], v[172:175], v[198:201], v[44:47]
	v_mfma_f32_16x16x32_bf16 v[36:39], v[180:183], v[198:201], v[36:39]
	v_mfma_f32_16x16x32_bf16 v[28:31], v[172:175], v[206:209], v[28:31]
	v_mfma_f32_16x16x32_bf16 v[20:23], v[180:183], v[206:209], v[20:23]
	v_mfma_f32_16x16x32_bf16 v[12:15], v[172:175], v[214:217], v[12:15]
	v_mfma_f32_16x16x32_bf16 v[4:7], v[180:183], v[214:217], v[4:7]
	s_setprio 0
	s_barrier
	s_add_i32 s51, s51, 2
	s_add_u32 s22, s22, 0x100
	s_addc_u32 s23, s23, 0
	s_add_u32 s49, s49, 0x100
	s_addc_u32 s50, s50, 0

; #define PG8_STAGE(bufoff, gbase, voff) do { _Pragma("unroll") for (int _i = 0; _i < 2; ++_i) \
;         __builtin_amdgcn_global_load_lds((const unsigned*)((const char*)(gbase) + (voff)[_i]), (PG8_LAS unsigned*)(lds + (bufoff) + ldsw + _i * 8192), 16, 0, 0); } while (0)
; #define PG8_LDA(dst, b, h) do { _Pragma("unroll") for (int m = 0; m < 4; ++m) _Pragma("unroll") for (int k = 0; k < 2; ++k) dst[m][k] = *(const PG8_LAS bf16x8*)(lds + PG8_SA(b, h) + aoff + m * 2048 + k * 1024); } while (0)
; #define PG8_LDB(dst, b, h) do { _Pragma("unroll") for (int n = 0; n < 2; ++n) _Pragma("unroll") for (int k = 0; k < 2; ++k) dst[n][k] = *(const PG8_LAS bf16x8*)(lds + PG8_SB(b, h) + boff + n * 2048 + k * 1024); } while (0)
; #define PG8_WAIT_V(n) asm volatile("s_waitcnt vmcnt(" #n ")" ::: "memory")
; #define PG8_WAIT_L(n) asm volatile("s_waitcnt lgkmcnt(" #n ")" ::: "memory")
; #define PG8_BAR __builtin_amdgcn_s_barrier()
; #define PG8_SCHED __builtin_amdgcn_sched_barrier(0)
; template <class Epi, class Sched, bool ALIGN_EPI = false, bool SP2 = false>
; __device__ __forceinline__ void gemm_phase(PG8_LAS unsigned char* lds, const Gemm g, const Sched& S, const Epi& E) {
;     ...
;         const bool has_next = S.next(ui + 1, nxt);
;         const char* nA = has_next ? (const char*)g.A + (size_t)nxt.pm * tstep : cA; const char* nB = has_next ? (const char*)g.Bt + (size_t)nxt.pn * tstep : cB;
;         for (int t = 0; t < nt; t += 2) {
;             const bool last = (t == nt - 2);
;             const char* a1 = cA + (size_t)(t + 1) * kstep;
;             const char* a2 = last ? nA : cA + (size_t)(t + 2) * kstep; const char* b2 = last ? nB : cB + (size_t)(t + 2) * kstep;
;             const char* a3 = a2 + kstep; const char* b3 = b2 + kstep;
;             if (last && has_next) S.a_ready(nxt);
;             if constexpr (SP2) {
;             PG8_LDB(B0, 0, 0); PG8_LDB(B1, 0, 1); PG8_SCHED; PG8_LDA(At, 0, 0); PG8_STAGE(PG8_SA(1, 1), a1 + hstep, voffA);
;             PG8_WAIT_V(8); PG8_WAIT_L(0); PG8_BAR; PG8_MMA(0, 0, At, B0); PG8_MMA(0, 1, At, B1); PG8_BAR; PG8_SCHED;
;             PG8_LDA(At, 0, 1); PG8_STAGE(PG8_SB(0, 0), b2, voffB); PG8_STAGE(PG8_SB(0, 1), b2 + hstep, voffB); PG8_STAGE(PG8_SA(0, 0), a2, voffA);
;             PG8_WAIT_V(8); PG8_WAIT_L(0); PG8_BAR; PG8_MMA(1, 0, At, B0); PG8_MMA(1, 1, At, B1); PG8_BAR; PG8_SCHED;
.LBB0_861:
	s_add_u32 s49, s24, 0x100
	s_addc_u32 s50, s25, 0
	s_mov_b32 s51, -2
	ds_read_b128 v[144:147], v153
	ds_read_b128 v[156:159], v153 offset:1024
	ds_read_b128 v[160:163], v153 offset:2048
	ds_read_b128 v[164:167], v153 offset:3072
	ds_read_b128 v[168:171], v154
	ds_read_b128 v[172:175], v154 offset:1024
	ds_read_b128 v[176:179], v154 offset:2048
	ds_read_b128 v[180:183], v154 offset:3072
	s_add_u32 s24, s22, 0x100
	s_addc_u32 s25, s23, 0
	s_cmp_eq_u32 s51, 40
	s_cselect_b32 s29, s5, s25
	s_cselect_b32 s28, s4, s24
	s_cselect_b32 s27, s21, s50
	s_cselect_b32 s26, s20, s49
	v_lshl_add_u64 v[148:149], s[22:23], 0, v[136:137]
	s_add_i32 m0, s35, 0xc000
	ds_read_b128 v[184:187], v155
	ds_read_b128 v[188:191], v155 offset:1024
	ds_read_b128 v[192:195], v155 offset:2048
	ds_read_b128 v[196:199], v155 offset:3072
	ds_read_b128 v[200:203], v155 offset:4096
	ds_read_b128 v[204:207], v155 offset:5120
	ds_read_b128 v[208:211], v155 offset:6144
	ds_read_b128 v[212:215], v155 offset:7168
	global_load_lds_dwordx4 v[148:149], off
	v_lshl_add_u64 v[148:149], s[22:23], 0, v[138:139]
	s_add_i32 m0, s35, 0xe000
	s_nop 0
	global_load_lds_dwordx4 v[148:149], off
	s_waitcnt vmcnt(8)
	s_waitcnt lgkmcnt(0)
	s_barrier
	s_setprio 1
	v_mfma_f32_16x16x32_bf16 v[124:127], v[144:147], v[184:187], 0
	v_mfma_f32_16x16x32_bf16 v[120:123], v[160:163], v[184:187], 0
	v_mfma_f32_16x16x32_bf16 v[108:111], v[144:147], v[192:195], 0
	v_mfma_f32_16x16x32_bf16 v[104:107], v[160:163], v[192:195], 0
	v_mfma_f32_16x16x32_bf16 v[92:95], v[144:147], v[200:203], 0
	v_mfma_f32_16x16x32_bf16 v[88:91], v[160:163], v[200:203], 0
	v_mfma_f32_16x16x32_bf16 v[76:79], v[144:147], v[208:211], 0
	v_mfma_f32_16x16x32_bf16 v[72:75], v[160:163], v[208:211], 0
	v_mfma_f32_16x16x32_bf16 v[124:127], v[156:159], v[188:191], v[124:127]
	v_mfma_f32_16x16x32_bf16 v[120:123], v[164:167], v[188:191], v[120:123]
	v_mfma_f32_16x16x32_bf16 v[108:111], v[156:159], v[196:199], v[108:111]
	v_mfma_f32_16x16x32_bf16 v[104:107], v[164:167], v[196:199], v[104:107]
	v_mfma_f32_16x16x32_bf16 v[92:95], v[156:159], v[204:207], v[92:95]
	v_mfma_f32_16x16x32_bf16 v[88:91], v[164:167], v[204:207], v[88:91]
	v_mfma_f32_16x16x32_bf16 v[76:79], v[156:159], v[212:215], v[76:79]
	v_mfma_f32_16x16x32_bf16 v[72:75], v[164:167], v[212:215], v[72:75]
	v_mfma_f32_16x16x32_bf16 v[116:119], v[168:171], v[184:187], 0
	v_mfma_f32_16x16x32_bf16 v[112:115], v[176:179], v[184:187], 0
	v_mfma_f32_16x16x32_bf16 v[100:103], v[168:171], v[192:195], 0
	v_mfma_f32_16x16x32_bf16 v[96:99], v[176:179], v[192:195], 0
	v_mfma_f32_16x16x32_bf16 v[84:87], v[168:171], v[200:203], 0
	v_mfma_f32_16x16x32_bf16 v[80:83], v[176:179], v[200:203], 0
	v_mfma_f32_16x16x32_bf16 v[68:71], v[168:171], v[208:211], 0
	v_mfma_f32_16x16x32_bf16 v[64:67], v[176:179], v[208:211], 0
	v_mfma_f32_16x16x32_bf16 v[116:119], v[172:175], v[188:191], v[116:119]
	v_mfma_f32_16x16x32_bf16 v[112:115], v[180:183], v[188:191], v[112:115]
	v_mfma_f32_16x16x32_bf16 v[100:103], v[172:175], v[196:199], v[100:103]
	v_mfma_f32_16x16x32_bf16 v[96:99], v[180:183], v[196:199], v[96:99]
	v_mfma_f32_16x16x32_bf16 v[84:87], v[172:175], v[204:207], v[84:87]
	v_mfma_f32_16x16x32_bf16 v[80:83], v[180:183], v[204:207], v[80:83]
	v_mfma_f32_16x16x32_bf16 v[68:71], v[172:175], v[212:215], v[68:71]
	v_mfma_f32_16x16x32_bf16 v[64:67], v[180:183], v[212:215], v[64:67]
	s_setprio 0
	s_barrier
	s_add_i32 s22, s43, s34
	v_lshl_add_u64 v[148:149], s[26:27], 0, v[130:131]
	s_mov_b32 m0, s22
	ds_read_b128 v[184:187], v155 offset:16384
	ds_read_b128 v[188:191], v155 offset:17408
	ds_read_b128 v[192:195], v155 offset:18432
	ds_read_b128 v[196:199], v155 offset:19456
	ds_read_b128 v[200:203], v155 offset:20480
	ds_read_b128 v[204:207], v155 offset:21504
	ds_read_b128 v[208:211], v155 offset:22528
	ds_read_b128 v[212:215], v155 offset:23552
	global_load_lds_dwordx4 v[148:149], off
	s_add_i32 m0, s22, 0x2000
	s_add_u32 s22, s26, 0xb0000
	v_lshl_add_u64 v[216:217], s[26:27], 0, v[134:135]
	s_addc_u32 s23, s27, 0
	s_add_i32 s52, s44, s34
	global_load_lds_dwordx4 v[216:217], off
	v_lshl_add_u64 v[218:219], s[22:23], 0, v[130:131]
	s_mov_b32 m0, s52
	v_lshl_add_u64 v[220:221], s[28:29], 0, v[132:133]
	global_load_lds_dwordx4 v[218:219], off
	v_lshl_add_u64 v[218:219], s[22:23], 0, v[134:135]
	s_add_i32 m0, s52, 0x2000
	s_nop 0
	global_load_lds_dwordx4 v[218:219], off
	v_lshl_add_u64 v[218:219], s[28:29], 0, v[128:129]
	s_mov_b32 m0, s35
	s_nop 0
	global_load_lds_dwordx4 v[218:219], off
	s_mov_b32 m0, s36
	s_nop 0
	global_load_lds_dwordx4 v[220:221], off
	s_waitcnt vmcnt(8)
	s_waitcnt lgkmcnt(0)
	s_barrier
; #define PG8_STAGE(bufoff, gbase, voff) do { _Pragma("unroll") for (int _i = 0; _i < 2; ++_i) \
;         __builtin_amdgcn_global_load_lds((const unsigned*)((const char*)(gbase) + (voff)[_i]), (PG8_LAS unsigned*)(lds + (bufoff) + ldsw + _i * 8192), 16, 0, 0); } while (0)
; #define PG8_LDA(dst, b, h) do { _Pragma("unroll") for (int m = 0; m < 4; ++m) _Pragma("unroll") for (int k = 0; k < 2; ++k) dst[m][k] = *(const PG8_LAS bf16x8*)(lds + PG8_SA(b, h) + aoff + m * 2048 + k * 1024); } while (0)
; #define PG8_LDB(dst, b, h) do { _Pragma("unroll") for (int n = 0; n < 2; ++n) _Pragma("unroll") for (int k = 0; k < 2; ++k) dst[n][k] = *(const PG8_LAS bf16x8*)(lds + PG8_SB(b, h) + boff + n * 2048 + k * 1024); } while (0)
; #define PG8_MMA(ai, bj, At, Bt) do { __builtin_amdgcn_s_setprio(1); _Pragma("unroll") for (int m = 0; m < 4; ++m) _Pragma("unroll") for (int n = 0; n < 2; ++n) _Pragma("unroll") for (int k = 0; k < 2; ++k) \
;         acc[ai][bj][m][n] = __builtin_amdgcn_mfma_f32_16x16x32_bf16(Bt[n][k], At[m][k], acc[ai][bj][m][n], 0, 0, 0); __builtin_amdgcn_s_setprio(0); } while (0)
; #define PG8_WAIT_V(n) asm volatile("s_waitcnt vmcnt(" #n ")" ::: "memory")
; #define PG8_WAIT_L(n) asm volatile("s_waitcnt lgkmcnt(" #n ")" ::: "memory")
; #define PG8_BAR __builtin_amdgcn_s_barrier()
; #define PG8_SCHED __builtin_amdgcn_sched_barrier(0)
; template <class Epi, class Sched, bool ALIGN_EPI = false, bool SP2 = false>
; __device__ __forceinline__ void gemm_phase(PG8_LAS unsigned char* lds, const Gemm g, const Sched& S, const Epi& E) {
;     ...
;             PG8_LDA(At, 0, 1); PG8_STAGE(PG8_SB(0, 0), b2, voffB); PG8_STAGE(PG8_SB(0, 1), b2 + hstep, voffB); PG8_STAGE(PG8_SA(0, 0), a2, voffA);
;             PG8_WAIT_V(8); PG8_WAIT_L(0); PG8_BAR; PG8_MMA(1, 0, At, B0); PG8_MMA(1, 1, At, B1); PG8_BAR; PG8_SCHED;
;             PG8_LDB(B0, 1, 0); PG8_LDB(B1, 1, 1); PG8_SCHED; PG8_LDA(At, 1, 0); PG8_STAGE(PG8_SA(0, 1), a2 + hstep, voffA);
;             PG8_WAIT_V(8); PG8_WAIT_L(0); PG8_BAR; PG8_MMA(0, 0, At, B0); PG8_MMA(0, 1, At, B1); PG8_BAR; PG8_SCHED;
	s_setprio 1
	v_mfma_f32_16x16x32_bf16 v[60:63], v[144:147], v[184:187], 0
	v_mfma_f32_16x16x32_bf16 v[56:59], v[160:163], v[184:187], 0
	v_mfma_f32_16x16x32_bf16 v[44:47], v[144:147], v[192:195], 0
	v_mfma_f32_16x16x32_bf16 v[40:43], v[160:163], v[192:195], 0
	v_mfma_f32_16x16x32_bf16 v[28:31], v[144:147], v[200:203], 0
	v_mfma_f32_16x16x32_bf16 v[24:27], v[160:163], v[200:203], 0
	v_mfma_f32_16x16x32_bf16 v[12:15], v[144:147], v[208:211], 0
	v_mfma_f32_16x16x32_bf16 v[8:11], v[160:163], v[208:211], 0
	v_mfma_f32_16x16x32_bf16 v[60:63], v[156:159], v[188:191], v[60:63]
	v_mfma_f32_16x16x32_bf16 v[56:59], v[164:167], v[188:191], v[56:59]
	v_mfma_f32_16x16x32_bf16 v[44:47], v[156:159], v[196:199], v[44:47]
	v_mfma_f32_16x16x32_bf16 v[40:43], v[164:167], v[196:199], v[40:43]
	v_mfma_f32_16x16x32_bf16 v[28:31], v[156:159], v[204:207], v[28:31]
	v_mfma_f32_16x16x32_bf16 v[24:27], v[164:167], v[204:207], v[24:27]
	v_mfma_f32_16x16x32_bf16 v[12:15], v[156:159], v[212:215], v[12:15]
	v_mfma_f32_16x16x32_bf16 v[8:11], v[164:167], v[212:215], v[8:11]
	v_mfma_f32_16x16x32_bf16 v[52:55], v[168:171], v[184:187], 0
	v_mfma_f32_16x16x32_bf16 v[48:51], v[176:179], v[184:187], 0
	v_mfma_f32_16x16x32_bf16 v[36:39], v[168:171], v[192:195], 0
	v_mfma_f32_16x16x32_bf16 v[32:35], v[176:179], v[192:195], 0
	v_mfma_f32_16x16x32_bf16 v[20:23], v[168:171], v[200:203], 0
	v_mfma_f32_16x16x32_bf16 v[16:19], v[176:179], v[200:203], 0
	v_mfma_f32_16x16x32_bf16 v[4:7], v[168:171], v[208:211], 0
	v_mfma_f32_16x16x32_bf16 v[0:3], v[176:179], v[208:211], 0
	v_mfma_f32_16x16x32_bf16 v[52:55], v[172:175], v[188:191], v[52:55]
	v_mfma_f32_16x16x32_bf16 v[48:51], v[180:183], v[188:191], v[48:51]
	v_mfma_f32_16x16x32_bf16 v[36:39], v[172:175], v[196:199], v[36:39]
	v_mfma_f32_16x16x32_bf16 v[32:35], v[180:183], v[196:199], v[32:35]
	v_mfma_f32_16x16x32_bf16 v[20:23], v[172:175], v[204:207], v[20:23]
	v_mfma_f32_16x16x32_bf16 v[16:19], v[180:183], v[204:207], v[16:19]
	v_mfma_f32_16x16x32_bf16 v[4:7], v[172:175], v[212:215], v[4:7]
	v_mfma_f32_16x16x32_bf16 v[0:3], v[180:183], v[212:215], v[0:3]
	s_setprio 0
	s_barrier
	s_add_i32 s52, 0, 0x18000
	s_add_i32 s53, 0, 0x1c000
	v_add_u32_e32 v164, s52, v151
	v_add_u32_e32 v180, s53, v151
	ds_read_b128 v[144:147], v164
	ds_read_b128 v[156:159], v164 offset:1024
	ds_read_b128 v[160:163], v164 offset:2048
	ds_read_b128 v[164:167], v164 offset:3072
	ds_read_b128 v[168:171], v180
	ds_read_b128 v[172:175], v180 offset:1024
	ds_read_b128 v[176:179], v180 offset:2048
	ds_read_b128 v[180:183], v180 offset:3072
	s_add_u32 s22, s28, 0xb0000
	s_addc_u32 s23, s29, 0
	s_mov_b32 m0, s37
	v_lshl_add_u64 v[222:223], s[22:23], 0, v[128:129]
	ds_read_b128 v[184:187], v155 offset:32768
	ds_read_b128 v[188:191], v155 offset:33792
	ds_read_b128 v[192:195], v155 offset:34816
	ds_read_b128 v[196:199], v155 offset:35840
	ds_read_b128 v[200:203], v155 offset:36864
	ds_read_b128 v[204:207], v155 offset:37888
	ds_read_b128 v[208:211], v155 offset:38912
	ds_read_b128 v[212:215], v155 offset:39936
	global_load_lds_dwordx4 v[222:223], off
	v_lshl_add_u64 v[222:223], s[22:23], 0, v[132:133]
	s_mov_b32 m0, s38
	s_nop 0
	global_load_lds_dwordx4 v[222:223], off
	s_waitcnt vmcnt(8)
	s_waitcnt lgkmcnt(0)
	s_barrier
	s_setprio 1
	v_mfma_f32_16x16x32_bf16 v[124:127], v[144:147], v[184:187], v[124:127]
	v_mfma_f32_16x16x32_bf16 v[120:123], v[160:163], v[184:187], v[120:123]
	v_mfma_f32_16x16x32_bf16 v[108:111], v[144:147], v[192:195], v[108:111]
	v_mfma_f32_16x16x32_bf16 v[104:107], v[160:163], v[192:195], v[104:107]
	v_mfma_f32_16x16x32_bf16 v[92:95], v[144:147], v[200:203], v[92:95]
	v_mfma_f32_16x16x32_bf16 v[88:91], v[160:163], v[200:203], v[88:91]
	v_mfma_f32_16x16x32_bf16 v[76:79], v[144:147], v[208:211], v[76:79]
	v_mfma_f32_16x16x32_bf16 v[72:75], v[160:163], v[208:211], v[72:75]
	v_mfma_f32_16x16x32_bf16 v[124:127], v[156:159], v[188:191], v[124:127]
	v_mfma_f32_16x16x32_bf16 v[120:123], v[164:167], v[188:191], v[120:123]
	v_mfma_f32_16x16x32_bf16 v[108:111], v[156:159], v[196:199], v[108:111]
	v_mfma_f32_16x16x32_bf16 v[104:107], v[164:167], v[196:199], v[104:107]
	v_mfma_f32_16x16x32_bf16 v[92:95], v[156:159], v[204:207], v[92:95]
	v_mfma_f32_16x16x32_bf16 v[88:91], v[164:167], v[204:207], v[88:91]
	v_mfma_f32_16x16x32_bf16 v[76:79], v[156:159], v[212:215], v[76:79]
	v_mfma_f32_16x16x32_bf16 v[72:75], v[164:167], v[212:215], v[72:75]
	v_mfma_f32_16x16x32_bf16 v[116:119], v[168:171], v[184:187], v[116:119]
	v_mfma_f32_16x16x32_bf16 v[112:115], v[176:179], v[184:187], v[112:115]
	v_mfma_f32_16x16x32_bf16 v[100:103], v[168:171], v[192:195], v[100:103]
	v_mfma_f32_16x16x32_bf16 v[96:99], v[176:179], v[192:195], v[96:99]
	v_mfma_f32_16x16x32_bf16 v[84:87], v[168:171], v[200:203], v[84:87]
	v_mfma_f32_16x16x32_bf16 v[80:83], v[176:179], v[200:203], v[80:83]
	v_mfma_f32_16x16x32_bf16 v[68:71], v[168:171], v[208:211], v[68:71]
	v_mfma_f32_16x16x32_bf16 v[64:67], v[176:179], v[208:211], v[64:67]
	v_mfma_f32_16x16x32_bf16 v[116:119], v[172:175], v[188:191], v[116:119]
	v_mfma_f32_16x16x32_bf16 v[112:115], v[180:183], v[188:191], v[112:115]
	v_mfma_f32_16x16x32_bf16 v[100:103], v[172:175], v[196:199], v[100:103]
	v_mfma_f32_16x16x32_bf16 v[96:99], v[180:183], v[196:199], v[96:99]
	v_mfma_f32_16x16x32_bf16 v[84:87], v[172:175], v[204:207], v[84:87]
	v_mfma_f32_16x16x32_bf16 v[80:83], v[180:183], v[204:207], v[80:83]
	v_mfma_f32_16x16x32_bf16 v[68:71], v[172:175], v[212:215], v[68:71]
	v_mfma_f32_16x16x32_bf16 v[64:67], v[180:183], v[212:215], v[64:67]
	s_setprio 0
	s_barrier
; #define PG8_STAGE(bufoff, gbase, voff) do { _Pragma("unroll") for (int _i = 0; _i < 2; ++_i) \
;         __builtin_amdgcn_global_load_lds((const unsigned*)((const char*)(gbase) + (voff)[_i]), (PG8_LAS unsigned*)(lds + (bufoff) + ldsw + _i * 8192), 16, 0, 0); } while (0)
; #define PG8_LDA(dst, b, h) do { _Pragma("unroll") for (int m = 0; m < 4; ++m) _Pragma("unroll") for (int k = 0; k < 2; ++k) dst[m][k] = *(const PG8_LAS bf16x8*)(lds + PG8_SA(b, h) + aoff + m * 2048 + k * 1024); } while (0)
; #define PG8_MMA(ai, bj, At, Bt) do { __builtin_amdgcn_s_setprio(1); _Pragma("unroll") for (int m = 0; m < 4; ++m) _Pragma("unroll") for (int n = 0; n < 2; ++n) _Pragma("unroll") for (int k = 0; k < 2; ++k) \
;         acc[ai][bj][m][n] = __builtin_amdgcn_mfma_f32_16x16x32_bf16(Bt[n][k], At[m][k], acc[ai][bj][m][n], 0, 0, 0); __builtin_amdgcn_s_setprio(0); } while (0)
; #define PG8_WAIT_V(n) asm volatile("s_waitcnt vmcnt(" #n ")" ::: "memory")
; #define PG8_WAIT_L(n) asm volatile("s_waitcnt lgkmcnt(" #n ")" ::: "memory")
; #define PG8_BAR __builtin_amdgcn_s_barrier()
; #define PG8_SCHED __builtin_amdgcn_sched_barrier(0)
; template <class Epi, class Sched, bool ALIGN_EPI = false, bool SP2 = false>
; __device__ __forceinline__ void gemm_phase(PG8_LAS unsigned char* lds, const Gemm g, const Sched& S, const Epi& E) {
;     ...
;             PG8_LDA(At, 1, 1); PG8_STAGE(PG8_SB(1, 0), b3, voffB); PG8_STAGE(PG8_SB(1, 1), b3 + hstep, voffB); PG8_STAGE(PG8_SA(1, 0), a3, voffA);
;             PG8_WAIT_V(8); PG8_WAIT_L(0); PG8_BAR; PG8_MMA(1, 0, At, B0); PG8_MMA(1, 1, At, B1); PG8_BAR; PG8_SCHED;
	s_add_i32 s22, s52, s34
	v_lshl_add_u64 v[148:149], v[148:149], 0, s[6:7]
	s_mov_b32 m0, s22
	ds_read_b128 v[184:187], v155 offset:49152
	ds_read_b128 v[188:191], v155 offset:50176
	ds_read_b128 v[192:195], v155 offset:51200
	ds_read_b128 v[196:199], v155 offset:52224
	ds_read_b128 v[200:203], v155 offset:53248
	ds_read_b128 v[204:207], v155 offset:54272
	ds_read_b128 v[208:211], v155 offset:55296
	ds_read_b128 v[212:215], v155 offset:56320
	global_load_lds_dwordx4 v[148:149], off
	s_add_i32 m0, s22, 0x2000
	s_add_u32 s22, s26, 0xb0080
	v_lshl_add_u64 v[148:149], v[216:217], 0, s[6:7]
	s_addc_u32 s23, s27, 0
	s_add_i32 s26, s53, s34
	global_load_lds_dwordx4 v[148:149], off
	v_lshl_add_u64 v[148:149], s[22:23], 0, v[130:131]
	s_mov_b32 m0, s26
	s_nop 0
	global_load_lds_dwordx4 v[148:149], off
	v_lshl_add_u64 v[148:149], s[22:23], 0, v[134:135]
	s_add_i32 m0, s26, 0x2000
	s_nop 0
	global_load_lds_dwordx4 v[148:149], off
	v_lshl_add_u64 v[148:149], v[218:219], 0, s[6:7]
	s_mov_b32 m0, s40
	s_nop 0
	global_load_lds_dwordx4 v[148:149], off
	v_lshl_add_u64 v[148:149], v[220:221], 0, s[6:7]
	s_mov_b32 m0, s41
	s_nop 0
	global_load_lds_dwordx4 v[148:149], off
	s_waitcnt vmcnt(8)
	s_waitcnt lgkmcnt(0)
	s_barrier
	s_setprio 1
	v_mfma_f32_16x16x32_bf16 v[60:63], v[144:147], v[184:187], v[60:63]
	v_mfma_f32_16x16x32_bf16 v[56:59], v[160:163], v[184:187], v[56:59]
	v_mfma_f32_16x16x32_bf16 v[44:47], v[144:147], v[192:195], v[44:47]
	v_mfma_f32_16x16x32_bf16 v[40:43], v[160:163], v[192:195], v[40:43]
	v_mfma_f32_16x16x32_bf16 v[28:31], v[144:147], v[200:203], v[28:31]
	v_mfma_f32_16x16x32_bf16 v[24:27], v[160:163], v[200:203], v[24:27]
	v_mfma_f32_16x16x32_bf16 v[12:15], v[144:147], v[208:211], v[12:15]
	v_mfma_f32_16x16x32_bf16 v[8:11], v[160:163], v[208:211], v[8:11]
	v_mfma_f32_16x16x32_bf16 v[60:63], v[156:159], v[188:191], v[60:63]
	v_mfma_f32_16x16x32_bf16 v[56:59], v[164:167], v[188:191], v[56:59]
	v_mfma_f32_16x16x32_bf16 v[44:47], v[156:159], v[196:199], v[44:47]
	v_mfma_f32_16x16x32_bf16 v[40:43], v[164:167], v[196:199], v[40:43]
	v_mfma_f32_16x16x32_bf16 v[28:31], v[156:159], v[204:207], v[28:31]
	v_mfma_f32_16x16x32_bf16 v[24:27], v[164:167], v[204:207], v[24:27]
	v_mfma_f32_16x16x32_bf16 v[12:15], v[156:159], v[212:215], v[12:15]
	v_mfma_f32_16x16x32_bf16 v[8:11], v[164:167], v[212:215], v[8:11]
	v_mfma_f32_16x16x32_bf16 v[52:55], v[168:171], v[184:187], v[52:55]
	v_mfma_f32_16x16x32_bf16 v[48:51], v[176:179], v[184:187], v[48:51]
	v_mfma_f32_16x16x32_bf16 v[36:39], v[168:171], v[192:195], v[36:39]
	v_mfma_f32_16x16x32_bf16 v[32:35], v[176:179], v[192:195], v[32:35]
	v_mfma_f32_16x16x32_bf16 v[20:23], v[168:171], v[200:203], v[20:23]
	v_mfma_f32_16x16x32_bf16 v[16:19], v[176:179], v[200:203], v[16:19]
	v_mfma_f32_16x16x32_bf16 v[4:7], v[168:171], v[208:211], v[4:7]
	v_mfma_f32_16x16x32_bf16 v[0:3], v[176:179], v[208:211], v[0:3]
	v_mfma_f32_16x16x32_bf16 v[52:55], v[172:175], v[188:191], v[52:55]
	v_mfma_f32_16x16x32_bf16 v[48:51], v[180:183], v[188:191], v[48:51]
	v_mfma_f32_16x16x32_bf16 v[36:39], v[172:175], v[196:199], v[36:39]
	v_mfma_f32_16x16x32_bf16 v[32:35], v[180:183], v[196:199], v[32:35]
	v_mfma_f32_16x16x32_bf16 v[20:23], v[172:175], v[204:207], v[20:23]
	v_mfma_f32_16x16x32_bf16 v[16:19], v[180:183], v[204:207], v[16:19]
	v_mfma_f32_16x16x32_bf16 v[4:7], v[172:175], v[212:215], v[4:7]
	v_mfma_f32_16x16x32_bf16 v[0:3], v[180:183], v[212:215], v[0:3]
	s_setprio 0
	s_barrier
	s_add_i32 s51, s51, 2
	s_add_u32 s49, s49, 0x100
	s_addc_u32 s50, s50, 0
	s_mov_b64 s[22:23], s[24:25]
